# v52 + EpiGates: the 16 UC words of an i-gate unit requested in two batches of 8 instead of 16 dependent loads
# baseline (speedup 1.0000x reference)
; __device__ __forceinline__ unsigned cvt_pk_bf16(float lo, float hi) { unsigned r; asm volatile("v_cvt_pk_bf16_f32 %0, %1, %2" : "=v"(r) : "v"(lo), "v"(hi)); return r; }
; __device__ __forceinline__ float sigmoid_f(float x) { return __builtin_amdgcn_rcpf(1.0f + __builtin_amdgcn_exp2f(-1.4426950409f * x)); }
; __device__ __forceinline__ float bf_lo(unsigned w) { return __uint_as_float(w << 16); }
;     __device__ __forceinline__ void operator()(const f32x4 (&acc)[2][2][4][2], const Unit& u, int wr, int wc, int fr, int fq) const {
;         const int row0 = u.pm * BM + wr * 64 + fr; const bool isA = u.pn < 8; const int col0 = (u.pn & 7) * BM + wc * 32 + 8 * fq;
;         const float* bsrc = isA ? b_a : b_i;
;         f32x4 bv[2][2], sv[2][2];
; #pragma unroll
;         for (int bj = 0; bj < 2; ++bj)
; #pragma unroll
;             for (int n = 0; n < 2; ++n) { bv[bj][n] = *(const f32x4*)(bsrc + col0 + bj * HALF + 4 * n); sv[bj][n] = *(const f32x4*)(sp + col0 + bj * HALF + 4 * n) * (-8.0f * 1.4426950409f); }
; #pragma unroll
;         for (int ai = 0; ai < 2; ++ai)
; #pragma unroll
;             for (int m = 0; m < 4; ++m) { const size_t off = (size_t)(row0 + ai * HALF + m * 16) * 2048 + col0;
; #pragma unroll
;                 for (int bj = 0; bj < 2; ++bj) { const f32x4 v0 = acc[ai][bj][m][0] + bv[bj][0], v1 = acc[ai][bj][m][1] + bv[bj][1]; float o[8];
;                     if (isA) {
; #pragma unroll
;                         for (int e = 0; e < 4; ++e) { o[e] = 1.0f - __builtin_amdgcn_exp2f(sigmoid_f(v0[e]) * sv[bj][0][e]); o[4 + e] = 1.0f - __builtin_amdgcn_exp2f(sigmoid_f(v1[e]) * sv[bj][1][e]); }
;                     } else {
;                         const u32x4 uw = *(const u32x4*)(UC + off + bj * HALF);
;                         o[0] = sigmoid_f(v0[0]) * bf_lo(uw.x); o[1] = sigmoid_f(v0[1]) * bf_hi(uw.x); o[2] = sigmoid_f(v0[2]) * bf_lo(uw.y); o[3] = sigmoid_f(v0[3]) * bf_hi(uw.y);
;                         o[4] = sigmoid_f(v1[0]) * bf_lo(uw.z); o[5] = sigmoid_f(v1[1]) * bf_hi(uw.z); o[6] = sigmoid_f(v1[2]) * bf_lo(uw.w); o[7] = sigmoid_f(v1[3]) * bf_hi(uw.w);
;                     }
;                     u32x4 w; w.x = cvt_pk_bf16(o[0], o[1]); w.y = cvt_pk_bf16(o[2], o[3]); w.z = cvt_pk_bf16(o[4], o[5]); w.w = cvt_pk_bf16(o[6], o[7]);
;                     if (isA) *(u32x4*)(OMA + off + bj * HALF) = w; else *(u32x4*)(GI + off + bj * HALF) = w; } }
.LBB0_339:
	s_cmp_gt_u32 s20, 7
	s_cselect_b64 s[12:13], -1, 0
	s_lshl_b32 s11, s20, 8
	s_and_b32 s11, s11, 0x700
	v_add_u32_e32 v172, s11, v198
	s_cmp_lt_u32 s20, 8
	v_ashrrev_i32_e32 v173, 31, v172
	s_cselect_b32 s15, s1, s19
	s_cselect_b32 s14, s0, s18
	v_lshlrev_b64 v[26:27], 2, v[172:173]
	v_lshl_add_u64 v[30:31], s[14:15], 0, v[26:27]
	v_lshl_add_u64 v[150:151], s[26:27], 0, v[26:27]
	global_load_dwordx4 v[42:45], v[30:31], off offset:16
	global_load_dwordx4 v[46:49], v[30:31], off
	global_load_dwordx4 v[154:157], v[150:151], off offset:16
	global_load_dwordx4 v[158:161], v[150:151], off
	global_load_dwordx4 v[26:29], v[30:31], off offset:528
	s_nop 0
	global_load_dwordx4 v[30:33], v[30:31], off offset:512
	s_nop 0
	global_load_dwordx4 v[146:149], v[150:151], off offset:528
	s_nop 0
	global_load_dwordx4 v[150:153], v[150:151], off offset:512
	v_lshl_add_u32 v174, s10, 8, v196
	v_ashrrev_i32_e32 v175, 31, v174
	v_lshlrev_b64 v[176:177], 11, v[174:175]
	v_lshl_add_u64 v[176:177], v[176:177], 0, v[172:173]
	s_mov_b64 s[10:11], -1
	s_and_b64 vcc, exec, s[12:13]
	v_lshl_add_u64 v[178:179], v[176:177], 1, s[46:47]
	s_waitcnt vmcnt(0)
	v_pk_add_f32 v[144:145], v[144:145], v[44:45]
	v_pk_add_f32 v[140:141], v[140:141], v[48:49]
	v_pk_add_f32 v[138:139], v[138:139], v[46:47]
	v_pk_add_f32 v[142:143], v[142:143], v[42:43]
	v_mul_f32_e32 v207, 0xbfb8aa3b, v138
	v_mul_f32_e32 v205, 0xbfb8aa3b, v139
	v_mul_f32_e32 v203, 0xbfb8aa3b, v140
	v_mul_f32_e32 v201, 0xbfb8aa3b, v141
	v_mul_f32_e32 v206, 0xbfb8aa3b, v142
	v_mul_f32_e32 v204, 0xbfb8aa3b, v143
	v_mul_f32_e32 v202, 0xbfb8aa3b, v144
	v_mul_f32_e32 v200, 0xbfb8aa3b, v145
	s_cbranch_vccz .Lgu_skip
	global_load_dwordx4 v[190:193], v[178:179], off
	global_load_dwordx4 v[208:211], v[178:179], off offset:256
	v_mov_b32_e32 v248, 0x10000
	v_mov_b32_e32 v249, 0
	v_lshl_add_u64 v[246:247], v[178:179], 0, v[248:249]
	global_load_dwordx4 v[212:215], v[246:247], off
	global_load_dwordx4 v[216:219], v[246:247], off offset:256
	v_mov_b32_e32 v248, 0x20000
	v_mov_b32_e32 v249, 0
	v_lshl_add_u64 v[244:245], v[178:179], 0, v[248:249]
	global_load_dwordx4 v[228:231], v[244:245], off
	global_load_dwordx4 v[232:235], v[244:245], off offset:256
	v_mov_b32_e32 v248, 0x30000
	v_mov_b32_e32 v249, 0
	v_lshl_add_u64 v[246:247], v[178:179], 0, v[248:249]
	global_load_dwordx4 v[236:239], v[246:247], off
	global_load_dwordx4 v[240:243], v[246:247], off offset:256
.Lgu_skip:
	s_cbranch_vccz .LBB0_341
	s_nop 0
	v_exp_f32_e32 v142, v207
	v_exp_f32_e32 v143, v205
	s_mov_b64 s[10:11], 0
	v_add_f32_e32 v142, 1.0, v142
	v_add_f32_e32 v143, 1.0, v143
	v_rcp_f32_e32 v142, v142
	v_rcp_f32_e32 v143, v143
	s_waitcnt vmcnt(7)
	v_mov_b64_e32 v[138:139], v[190:191]
	v_mov_b64_e32 v[140:141], v[192:193]
	v_lshlrev_b32_e32 v144, 16, v138
	v_and_b32_e32 v145, 0xffff0000, v138
	v_exp_f32_e32 v138, v203
	v_pk_mul_f32 v[180:181], v[142:143], v[144:145]
	v_add_f32_e32 v138, 1.0, v138
	v_rcp_f32_e32 v142, v138
	v_exp_f32_e32 v138, v201
	s_nop 0
	v_add_f32_e32 v138, 1.0, v138
	v_rcp_f32_e32 v143, v138
	v_lshlrev_b32_e32 v138, 16, v139
	v_and_b32_e32 v139, 0xffff0000, v139
	v_pk_mul_f32 v[182:183], v[142:143], v[138:139]
	v_exp_f32_e32 v138, v206
	v_exp_f32_e32 v139, v204
	v_lshlrev_b32_e32 v142, 16, v140
	v_and_b32_e32 v143, 0xffff0000, v140
	v_add_f32_e32 v138, 1.0, v138
	v_add_f32_e32 v139, 1.0, v139
	v_rcp_f32_e32 v138, v138
	v_rcp_f32_e32 v139, v139
	v_lshlrev_b32_e32 v140, 16, v141
	v_and_b32_e32 v141, 0xffff0000, v141
	v_pk_mul_f32 v[184:185], v[138:139], v[142:143]
	v_exp_f32_e32 v138, v202
	v_exp_f32_e32 v139, v200
	v_add_f32_e32 v138, 1.0, v138
	v_add_f32_e32 v139, 1.0, v139
	v_rcp_f32_e32 v138, v138
	v_rcp_f32_e32 v139, v139
	s_nop 0
	v_pk_mul_f32 v[194:195], v[138:139], v[140:141]

; __device__ __forceinline__ unsigned cvt_pk_bf16(float lo, float hi) { unsigned r; asm volatile("v_cvt_pk_bf16_f32 %0, %1, %2" : "=v"(r) : "v"(lo), "v"(hi)); return r; }
; __device__ __forceinline__ float sigmoid_f(float x) { return __builtin_amdgcn_rcpf(1.0f + __builtin_amdgcn_exp2f(-1.4426950409f * x)); }
; __device__ __forceinline__ float bf_lo(unsigned w) { return __uint_as_float(w << 16); }
; __device__ __forceinline__ float bf_hi(unsigned w) { return __uint_as_float(w & 0xffff0000u); }
;     __device__ __forceinline__ void operator()(const f32x4 (&acc)[2][2][4][2], const Unit& u, int wr, int wc, int fr, int fq) const {
;     ...
;             for (int m = 0; m < 4; ++m) { const size_t off = (size_t)(row0 + ai * HALF + m * 16) * 2048 + col0;
; #pragma unroll
;                 for (int bj = 0; bj < 2; ++bj) { const f32x4 v0 = acc[ai][bj][m][0] + bv[bj][0], v1 = acc[ai][bj][m][1] + bv[bj][1]; float o[8];
;                     if (isA) {
; #pragma unroll
;                         for (int e = 0; e < 4; ++e) { o[e] = 1.0f - __builtin_amdgcn_exp2f(sigmoid_f(v0[e]) * sv[bj][0][e]); o[4 + e] = 1.0f - __builtin_amdgcn_exp2f(sigmoid_f(v1[e]) * sv[bj][1][e]); }
;                     } else {
;                         const u32x4 uw = *(const u32x4*)(UC + off + bj * HALF);
;                         o[0] = sigmoid_f(v0[0]) * bf_lo(uw.x); o[1] = sigmoid_f(v0[1]) * bf_hi(uw.x); o[2] = sigmoid_f(v0[2]) * bf_lo(uw.y); o[3] = sigmoid_f(v0[3]) * bf_hi(uw.y);
;                         o[4] = sigmoid_f(v1[0]) * bf_lo(uw.z); o[5] = sigmoid_f(v1[1]) * bf_hi(uw.z); o[6] = sigmoid_f(v1[2]) * bf_lo(uw.w); o[7] = sigmoid_f(v1[3]) * bf_hi(uw.w);
;                     }
;                     u32x4 w; w.x = cvt_pk_bf16(o[0], o[1]); w.y = cvt_pk_bf16(o[2], o[3]); w.z = cvt_pk_bf16(o[4], o[5]); w.w = cvt_pk_bf16(o[6], o[7]);
;                     if (isA) *(u32x4*)(OMA + off + bj * HALF) = w; else *(u32x4*)(GI + off + bj * HALF) = w; } }
.LBB0_343:
	v_cvt_pk_bf16_f32 v156, v180, v181
	v_lshl_add_u64 v[154:155], v[176:177], 1, s[44:45]
	v_cvt_pk_bf16_f32 v157, v182, v183
	v_cvt_pk_bf16_f32 v158, v184, v185
	v_cvt_pk_bf16_f32 v159, v194, v195
	global_store_dwordx4 v[154:155], v[156:159], off
	v_pk_add_f32 v[136:137], v[136:137], v[32:33]
	v_pk_add_f32 v[134:135], v[134:135], v[30:31]
	v_pk_add_f32 v[132:133], v[132:133], v[28:29]
	v_pk_add_f32 v[130:131], v[130:131], v[26:27]
	v_cndmask_b32_e64 v156, 0, 1, s[12:13]
	s_mov_b64 s[10:11], -1
	v_cmp_ne_u32_e64 s[40:41], 1, v156
	s_andn2_b64 vcc, exec, s[12:13]
	v_mul_f32_e32 v195, 0xbfb8aa3b, v134
	v_mul_f32_e32 v185, 0xbfb8aa3b, v135
	v_mul_f32_e32 v183, 0xbfb8aa3b, v136
	v_mul_f32_e32 v181, 0xbfb8aa3b, v137
	v_mul_f32_e32 v194, 0xbfb8aa3b, v130
	v_mul_f32_e32 v184, 0xbfb8aa3b, v131
	v_mul_f32_e32 v182, 0xbfb8aa3b, v132
	v_mul_f32_e32 v180, 0xbfb8aa3b, v133
	s_cbranch_vccnz .LBB0_345
	s_nop 0
	v_exp_f32_e32 v134, v195
	v_exp_f32_e32 v135, v185
	s_mov_b64 s[10:11], 0
	v_add_f32_e32 v134, 1.0, v134
	v_add_f32_e32 v135, 1.0, v135
	v_rcp_f32_e32 v134, v134
	v_rcp_f32_e32 v135, v135
	s_waitcnt vmcnt(6)
	v_mov_b64_e32 v[130:131], v[208:209]
	v_mov_b64_e32 v[132:133], v[210:211]
	v_lshlrev_b32_e32 v136, 16, v130
	v_and_b32_e32 v137, 0xffff0000, v130
	v_exp_f32_e32 v130, v183
	v_pk_mul_f32 v[156:157], v[134:135], v[136:137]
	v_add_f32_e32 v130, 1.0, v130
	v_rcp_f32_e32 v134, v130
	v_exp_f32_e32 v130, v181
	s_nop 0
	v_add_f32_e32 v130, 1.0, v130
	v_rcp_f32_e32 v135, v130
	v_lshlrev_b32_e32 v130, 16, v131
	v_and_b32_e32 v131, 0xffff0000, v131
	v_pk_mul_f32 v[158:159], v[134:135], v[130:131]
	v_exp_f32_e32 v130, v194
	v_exp_f32_e32 v131, v184
	v_lshlrev_b32_e32 v134, 16, v132
	v_and_b32_e32 v135, 0xffff0000, v132
	v_add_f32_e32 v130, 1.0, v130
	v_add_f32_e32 v131, 1.0, v131
	v_rcp_f32_e32 v130, v130
	v_rcp_f32_e32 v131, v131
	v_lshlrev_b32_e32 v132, 16, v133
	v_and_b32_e32 v133, 0xffff0000, v133
	v_pk_mul_f32 v[160:161], v[130:131], v[134:135]
	v_exp_f32_e32 v130, v182
	v_exp_f32_e32 v131, v180
	v_add_f32_e32 v130, 1.0, v130
	v_add_f32_e32 v131, 1.0, v131
	v_rcp_f32_e32 v130, v130
	v_rcp_f32_e32 v131, v131
	s_nop 0
	v_pk_mul_f32 v[176:177], v[130:131], v[132:133]

; __device__ __forceinline__ unsigned cvt_pk_bf16(float lo, float hi) { unsigned r; asm volatile("v_cvt_pk_bf16_f32 %0, %1, %2" : "=v"(r) : "v"(lo), "v"(hi)); return r; }
; __device__ __forceinline__ float sigmoid_f(float x) { return __builtin_amdgcn_rcpf(1.0f + __builtin_amdgcn_exp2f(-1.4426950409f * x)); }
; __device__ __forceinline__ float bf_lo(unsigned w) { return __uint_as_float(w << 16); }
; __device__ __forceinline__ float bf_hi(unsigned w) { return __uint_as_float(w & 0xffff0000u); }
;     __device__ __forceinline__ void operator()(const f32x4 (&acc)[2][2][4][2], const Unit& u, int wr, int wc, int fr, int fq) const {
;     ...
;             for (int m = 0; m < 4; ++m) { const size_t off = (size_t)(row0 + ai * HALF + m * 16) * 2048 + col0;
; #pragma unroll
;                 for (int bj = 0; bj < 2; ++bj) { const f32x4 v0 = acc[ai][bj][m][0] + bv[bj][0], v1 = acc[ai][bj][m][1] + bv[bj][1]; float o[8];
;                     if (isA) {
; #pragma unroll
;                         for (int e = 0; e < 4; ++e) { o[e] = 1.0f - __builtin_amdgcn_exp2f(sigmoid_f(v0[e]) * sv[bj][0][e]); o[4 + e] = 1.0f - __builtin_amdgcn_exp2f(sigmoid_f(v1[e]) * sv[bj][1][e]); }
;                     } else {
;                         const u32x4 uw = *(const u32x4*)(UC + off + bj * HALF);
;                         o[0] = sigmoid_f(v0[0]) * bf_lo(uw.x); o[1] = sigmoid_f(v0[1]) * bf_hi(uw.x); o[2] = sigmoid_f(v0[2]) * bf_lo(uw.y); o[3] = sigmoid_f(v0[3]) * bf_hi(uw.y);
;                         o[4] = sigmoid_f(v1[0]) * bf_lo(uw.z); o[5] = sigmoid_f(v1[1]) * bf_hi(uw.z); o[6] = sigmoid_f(v1[2]) * bf_lo(uw.w); o[7] = sigmoid_f(v1[3]) * bf_hi(uw.w);
;                     }
;                     u32x4 w; w.x = cvt_pk_bf16(o[0], o[1]); w.y = cvt_pk_bf16(o[2], o[3]); w.z = cvt_pk_bf16(o[4], o[5]); w.w = cvt_pk_bf16(o[6], o[7]);
;                     if (isA) *(u32x4*)(OMA + off + bj * HALF) = w; else *(u32x4*)(GI + off + bj * HALF) = w; } }
.LBB0_347:
	v_cvt_pk_bf16_f32 v146, v156, v157
	v_cvt_pk_bf16_f32 v147, v158, v159
	v_cvt_pk_bf16_f32 v148, v160, v161
	v_cvt_pk_bf16_f32 v149, v176, v177
	global_store_dwordx4 v[154:155], v[146:149], off offset:256
	v_pk_add_f32 v[128:129], v[128:129], v[48:49]
	v_pk_add_f32 v[126:127], v[126:127], v[46:47]
	v_or_b32_e32 v146, 16, v174
	v_ashrrev_i32_e32 v147, 31, v146
	v_lshlrev_b64 v[146:147], 11, v[146:147]
	v_lshl_add_u64 v[146:147], v[146:147], 0, v[172:173]
	v_pk_add_f32 v[124:125], v[124:125], v[44:45]
	v_pk_add_f32 v[148:149], v[122:123], v[42:43]
	s_mov_b64 s[10:11], -1
	s_and_b64 vcc, exec, s[40:41]
	v_lshl_add_u64 v[122:123], v[146:147], 1, s[46:47]
	v_mul_f32_e32 v157, 0xbfb8aa3b, v126
	v_mul_f32_e32 v155, 0xbfb8aa3b, v127
	v_mul_f32_e32 v153, 0xbfb8aa3b, v128
	v_mul_f32_e32 v151, 0xbfb8aa3b, v129
	v_mul_f32_e32 v156, 0xbfb8aa3b, v148
	v_mul_f32_e32 v154, 0xbfb8aa3b, v149
	v_mul_f32_e32 v152, 0xbfb8aa3b, v124
	v_mul_f32_e32 v150, 0xbfb8aa3b, v125
	s_cbranch_vccnz .LBB0_349
	s_nop 0
	v_exp_f32_e32 v124, v157
	v_exp_f32_e32 v125, v155
	s_mov_b64 s[10:11], 0
	v_add_f32_e32 v124, 1.0, v124
	v_add_f32_e32 v125, 1.0, v125
	v_rcp_f32_e32 v124, v124
	v_rcp_f32_e32 v125, v125
	s_waitcnt vmcnt(5)
	v_mov_b64_e32 v[158:159], v[212:213]
	v_mov_b64_e32 v[160:161], v[214:215]
	v_lshlrev_b32_e32 v126, 16, v158
	v_and_b32_e32 v127, 0xffff0000, v158
	v_pk_mul_f32 v[124:125], v[124:125], v[126:127]
	v_exp_f32_e32 v126, v153
	v_exp_f32_e32 v127, v151
	v_lshlrev_b32_e32 v128, 16, v159
	v_and_b32_e32 v129, 0xffff0000, v159
	v_add_f32_e32 v126, 1.0, v126
	v_add_f32_e32 v127, 1.0, v127
	v_rcp_f32_e32 v126, v126
	v_rcp_f32_e32 v127, v127
	v_lshlrev_b32_e32 v148, 16, v160
	v_and_b32_e32 v149, 0xffff0000, v160
	v_lshlrev_b32_e32 v158, 16, v161
	v_pk_mul_f32 v[126:127], v[126:127], v[128:129]
	v_exp_f32_e32 v128, v156
	v_exp_f32_e32 v129, v154
	v_and_b32_e32 v159, 0xffff0000, v161
	v_add_f32_e32 v128, 1.0, v128
	v_add_f32_e32 v129, 1.0, v129
	v_rcp_f32_e32 v128, v128
	v_rcp_f32_e32 v129, v129
	s_nop 0
	v_pk_mul_f32 v[128:129], v[128:129], v[148:149]
	v_exp_f32_e32 v148, v152
	v_exp_f32_e32 v149, v150
	v_add_f32_e32 v148, 1.0, v148
	v_add_f32_e32 v149, 1.0, v149
	v_rcp_f32_e32 v148, v148
	v_rcp_f32_e32 v149, v149
	s_nop 0
	v_pk_mul_f32 v[148:149], v[148:149], v[158:159]

; __device__ __forceinline__ unsigned cvt_pk_bf16(float lo, float hi) { unsigned r; asm volatile("v_cvt_pk_bf16_f32 %0, %1, %2" : "=v"(r) : "v"(lo), "v"(hi)); return r; }
; __device__ __forceinline__ float sigmoid_f(float x) { return __builtin_amdgcn_rcpf(1.0f + __builtin_amdgcn_exp2f(-1.4426950409f * x)); }
; __device__ __forceinline__ float bf_lo(unsigned w) { return __uint_as_float(w << 16); }
; __device__ __forceinline__ float bf_hi(unsigned w) { return __uint_as_float(w & 0xffff0000u); }
;     __device__ __forceinline__ void operator()(const f32x4 (&acc)[2][2][4][2], const Unit& u, int wr, int wc, int fr, int fq) const {
;     ...
;             for (int m = 0; m < 4; ++m) { const size_t off = (size_t)(row0 + ai * HALF + m * 16) * 2048 + col0;
; #pragma unroll
;                 for (int bj = 0; bj < 2; ++bj) { const f32x4 v0 = acc[ai][bj][m][0] + bv[bj][0], v1 = acc[ai][bj][m][1] + bv[bj][1]; float o[8];
;                     if (isA) {
; #pragma unroll
;                         for (int e = 0; e < 4; ++e) { o[e] = 1.0f - __builtin_amdgcn_exp2f(sigmoid_f(v0[e]) * sv[bj][0][e]); o[4 + e] = 1.0f - __builtin_amdgcn_exp2f(sigmoid_f(v1[e]) * sv[bj][1][e]); }
;                     } else {
;                         const u32x4 uw = *(const u32x4*)(UC + off + bj * HALF);
;                         o[0] = sigmoid_f(v0[0]) * bf_lo(uw.x); o[1] = sigmoid_f(v0[1]) * bf_hi(uw.x); o[2] = sigmoid_f(v0[2]) * bf_lo(uw.y); o[3] = sigmoid_f(v0[3]) * bf_hi(uw.y);
;                         o[4] = sigmoid_f(v1[0]) * bf_lo(uw.z); o[5] = sigmoid_f(v1[1]) * bf_hi(uw.z); o[6] = sigmoid_f(v1[2]) * bf_lo(uw.w); o[7] = sigmoid_f(v1[3]) * bf_hi(uw.w);
;                     }
;                     u32x4 w; w.x = cvt_pk_bf16(o[0], o[1]); w.y = cvt_pk_bf16(o[2], o[3]); w.z = cvt_pk_bf16(o[4], o[5]); w.w = cvt_pk_bf16(o[6], o[7]);
;                     if (isA) *(u32x4*)(OMA + off + bj * HALF) = w; else *(u32x4*)(GI + off + bj * HALF) = w; } }
.LBB0_351:
	v_pk_add_f32 v[120:121], v[120:121], v[32:33]
	v_pk_add_f32 v[118:119], v[118:119], v[30:31]
	v_pk_add_f32 v[116:117], v[116:117], v[28:29]
	v_pk_add_f32 v[114:115], v[114:115], v[26:27]
	v_cvt_pk_bf16_f32 v150, v124, v125
	v_cvt_pk_bf16_f32 v151, v126, v127
	v_cvt_pk_bf16_f32 v152, v128, v129
	v_cvt_pk_bf16_f32 v153, v148, v149
	v_lshl_add_u64 v[124:125], v[146:147], 1, s[44:45]
	s_mov_b64 s[10:11], -1
	s_and_b64 vcc, exec, s[40:41]
	v_mul_f32_e32 v149, 0xbfb8aa3b, v118
	v_mul_f32_e32 v147, 0xbfb8aa3b, v119
	v_mul_f32_e32 v129, 0xbfb8aa3b, v120
	v_mul_f32_e32 v127, 0xbfb8aa3b, v121
	v_mul_f32_e32 v148, 0xbfb8aa3b, v114
	v_mul_f32_e32 v146, 0xbfb8aa3b, v115
	v_mul_f32_e32 v128, 0xbfb8aa3b, v116
	v_mul_f32_e32 v126, 0xbfb8aa3b, v117
	global_store_dwordx4 v[124:125], v[150:153], off
	s_cbranch_vccnz .LBB0_353
	s_nop 0
	v_exp_f32_e32 v114, v149
	v_exp_f32_e32 v115, v147
	s_mov_b64 s[10:11], 0
	v_add_f32_e32 v114, 1.0, v114
	v_add_f32_e32 v115, 1.0, v115
	v_rcp_f32_e32 v114, v114
	v_rcp_f32_e32 v115, v115
	s_waitcnt vmcnt(4)
	v_mov_b64_e32 v[118:119], v[216:217]
	v_mov_b64_e32 v[120:121], v[218:219]
	v_lshlrev_b32_e32 v116, 16, v118
	v_and_b32_e32 v117, 0xffff0000, v118
	v_pk_mul_f32 v[114:115], v[114:115], v[116:117]
	v_exp_f32_e32 v116, v129
	v_exp_f32_e32 v117, v127
	v_lshlrev_b32_e32 v118, 16, v119
	v_and_b32_e32 v119, 0xffff0000, v119
	v_add_f32_e32 v116, 1.0, v116
	v_add_f32_e32 v117, 1.0, v117
	v_rcp_f32_e32 v116, v116
	v_rcp_f32_e32 v117, v117
	v_lshlrev_b32_e32 v122, 16, v120
	v_and_b32_e32 v123, 0xffff0000, v120
	v_exp_f32_e32 v120, v128
	v_pk_mul_f32 v[116:117], v[116:117], v[118:119]
	v_exp_f32_e32 v118, v148
	v_exp_f32_e32 v119, v146
	v_add_f32_e32 v120, 1.0, v120
	v_add_f32_e32 v118, 1.0, v118
	v_add_f32_e32 v119, 1.0, v119
	v_rcp_f32_e32 v118, v118
	v_rcp_f32_e32 v119, v119
	s_nop 0
	v_pk_mul_f32 v[118:119], v[118:119], v[122:123]
	v_rcp_f32_e32 v122, v120
	v_exp_f32_e32 v120, v126
	s_nop 0
	v_add_f32_e32 v120, 1.0, v120
	v_rcp_f32_e32 v123, v120
	v_lshlrev_b32_e32 v120, 16, v121
	v_and_b32_e32 v121, 0xffff0000, v121
	v_pk_mul_f32 v[120:121], v[122:123], v[120:121]

; __device__ __forceinline__ unsigned cvt_pk_bf16(float lo, float hi) { unsigned r; asm volatile("v_cvt_pk_bf16_f32 %0, %1, %2" : "=v"(r) : "v"(lo), "v"(hi)); return r; }
; __device__ __forceinline__ float sigmoid_f(float x) { return __builtin_amdgcn_rcpf(1.0f + __builtin_amdgcn_exp2f(-1.4426950409f * x)); }
; __device__ __forceinline__ float bf_lo(unsigned w) { return __uint_as_float(w << 16); }
; __device__ __forceinline__ float bf_hi(unsigned w) { return __uint_as_float(w & 0xffff0000u); }
;     __device__ __forceinline__ void operator()(const f32x4 (&acc)[2][2][4][2], const Unit& u, int wr, int wc, int fr, int fq) const {
;     ...
;             for (int m = 0; m < 4; ++m) { const size_t off = (size_t)(row0 + ai * HALF + m * 16) * 2048 + col0;
; #pragma unroll
;                 for (int bj = 0; bj < 2; ++bj) { const f32x4 v0 = acc[ai][bj][m][0] + bv[bj][0], v1 = acc[ai][bj][m][1] + bv[bj][1]; float o[8];
;                     if (isA) {
; #pragma unroll
;                         for (int e = 0; e < 4; ++e) { o[e] = 1.0f - __builtin_amdgcn_exp2f(sigmoid_f(v0[e]) * sv[bj][0][e]); o[4 + e] = 1.0f - __builtin_amdgcn_exp2f(sigmoid_f(v1[e]) * sv[bj][1][e]); }
;                     } else {
;                         const u32x4 uw = *(const u32x4*)(UC + off + bj * HALF);
;                         o[0] = sigmoid_f(v0[0]) * bf_lo(uw.x); o[1] = sigmoid_f(v0[1]) * bf_hi(uw.x); o[2] = sigmoid_f(v0[2]) * bf_lo(uw.y); o[3] = sigmoid_f(v0[3]) * bf_hi(uw.y);
;                         o[4] = sigmoid_f(v1[0]) * bf_lo(uw.z); o[5] = sigmoid_f(v1[1]) * bf_hi(uw.z); o[6] = sigmoid_f(v1[2]) * bf_lo(uw.w); o[7] = sigmoid_f(v1[3]) * bf_hi(uw.w);
;                     }
;                     u32x4 w; w.x = cvt_pk_bf16(o[0], o[1]); w.y = cvt_pk_bf16(o[2], o[3]); w.z = cvt_pk_bf16(o[4], o[5]); w.w = cvt_pk_bf16(o[6], o[7]);
;                     if (isA) *(u32x4*)(OMA + off + bj * HALF) = w; else *(u32x4*)(GI + off + bj * HALF) = w; } }
.LBB0_355:
	v_cvt_pk_bf16_f32 v114, v114, v115
	v_cvt_pk_bf16_f32 v115, v116, v117
	v_cvt_pk_bf16_f32 v116, v118, v119
	v_cvt_pk_bf16_f32 v117, v120, v121
	global_store_dwordx4 v[124:125], v[114:117], off offset:256
	v_pk_add_f32 v[112:113], v[112:113], v[48:49]
	v_pk_add_f32 v[110:111], v[110:111], v[46:47]
	v_or_b32_e32 v114, 32, v174
	v_ashrrev_i32_e32 v115, 31, v114
	v_lshlrev_b64 v[114:115], 11, v[114:115]
	v_lshl_add_u64 v[114:115], v[114:115], 0, v[172:173]
	v_pk_add_f32 v[108:109], v[108:109], v[44:45]
	v_pk_add_f32 v[116:117], v[106:107], v[42:43]
	s_mov_b64 s[10:11], -1
	s_and_b64 vcc, exec, s[40:41]
	v_lshl_add_u64 v[106:107], v[114:115], 1, s[46:47]
	v_mul_f32_e32 v125, 0xbfb8aa3b, v110
	v_mul_f32_e32 v123, 0xbfb8aa3b, v111
	v_mul_f32_e32 v121, 0xbfb8aa3b, v112
	v_mul_f32_e32 v119, 0xbfb8aa3b, v113
	v_mul_f32_e32 v124, 0xbfb8aa3b, v116
	v_mul_f32_e32 v122, 0xbfb8aa3b, v117
	v_mul_f32_e32 v120, 0xbfb8aa3b, v108
	v_mul_f32_e32 v118, 0xbfb8aa3b, v109
	s_cbranch_vccnz .LBB0_357
	s_nop 0
	v_exp_f32_e32 v108, v125
	v_exp_f32_e32 v109, v123
	s_mov_b64 s[10:11], 0
	v_add_f32_e32 v108, 1.0, v108
	v_add_f32_e32 v109, 1.0, v109
	v_rcp_f32_e32 v108, v108
	v_rcp_f32_e32 v109, v109
	s_waitcnt vmcnt(3)
	v_mov_b64_e32 v[126:127], v[228:229]
	v_mov_b64_e32 v[128:129], v[230:231]
	v_lshlrev_b32_e32 v110, 16, v126
	v_and_b32_e32 v111, 0xffff0000, v126
	v_pk_mul_f32 v[108:109], v[108:109], v[110:111]
	v_exp_f32_e32 v110, v121
	v_exp_f32_e32 v111, v119
	v_lshlrev_b32_e32 v112, 16, v127
	v_and_b32_e32 v113, 0xffff0000, v127
	v_add_f32_e32 v110, 1.0, v110
	v_add_f32_e32 v111, 1.0, v111
	v_rcp_f32_e32 v110, v110
	v_rcp_f32_e32 v111, v111
	v_lshlrev_b32_e32 v116, 16, v128
	v_and_b32_e32 v117, 0xffff0000, v128
	v_lshlrev_b32_e32 v126, 16, v129
	v_pk_mul_f32 v[110:111], v[110:111], v[112:113]
	v_exp_f32_e32 v112, v124
	v_exp_f32_e32 v113, v122
	v_and_b32_e32 v127, 0xffff0000, v129
	v_add_f32_e32 v112, 1.0, v112
	v_add_f32_e32 v113, 1.0, v113
	v_rcp_f32_e32 v112, v112
	v_rcp_f32_e32 v113, v113
	s_nop 0
	v_pk_mul_f32 v[112:113], v[112:113], v[116:117]
	v_exp_f32_e32 v116, v120
	v_exp_f32_e32 v117, v118
	v_add_f32_e32 v116, 1.0, v116
	v_add_f32_e32 v117, 1.0, v117
	v_rcp_f32_e32 v116, v116
	v_rcp_f32_e32 v117, v117
	s_nop 0
	v_pk_mul_f32 v[116:117], v[116:117], v[126:127]

; __device__ __forceinline__ unsigned cvt_pk_bf16(float lo, float hi) { unsigned r; asm volatile("v_cvt_pk_bf16_f32 %0, %1, %2" : "=v"(r) : "v"(lo), "v"(hi)); return r; }
; __device__ __forceinline__ float sigmoid_f(float x) { return __builtin_amdgcn_rcpf(1.0f + __builtin_amdgcn_exp2f(-1.4426950409f * x)); }
; __device__ __forceinline__ float bf_lo(unsigned w) { return __uint_as_float(w << 16); }
; __device__ __forceinline__ float bf_hi(unsigned w) { return __uint_as_float(w & 0xffff0000u); }
;     __device__ __forceinline__ void operator()(const f32x4 (&acc)[2][2][4][2], const Unit& u, int wr, int wc, int fr, int fq) const {
;     ...
;             for (int m = 0; m < 4; ++m) { const size_t off = (size_t)(row0 + ai * HALF + m * 16) * 2048 + col0;
; #pragma unroll
;                 for (int bj = 0; bj < 2; ++bj) { const f32x4 v0 = acc[ai][bj][m][0] + bv[bj][0], v1 = acc[ai][bj][m][1] + bv[bj][1]; float o[8];
;                     if (isA) {
; #pragma unroll
;                         for (int e = 0; e < 4; ++e) { o[e] = 1.0f - __builtin_amdgcn_exp2f(sigmoid_f(v0[e]) * sv[bj][0][e]); o[4 + e] = 1.0f - __builtin_amdgcn_exp2f(sigmoid_f(v1[e]) * sv[bj][1][e]); }
;                     } else {
;                         const u32x4 uw = *(const u32x4*)(UC + off + bj * HALF);
;                         o[0] = sigmoid_f(v0[0]) * bf_lo(uw.x); o[1] = sigmoid_f(v0[1]) * bf_hi(uw.x); o[2] = sigmoid_f(v0[2]) * bf_lo(uw.y); o[3] = sigmoid_f(v0[3]) * bf_hi(uw.y);
;                         o[4] = sigmoid_f(v1[0]) * bf_lo(uw.z); o[5] = sigmoid_f(v1[1]) * bf_hi(uw.z); o[6] = sigmoid_f(v1[2]) * bf_lo(uw.w); o[7] = sigmoid_f(v1[3]) * bf_hi(uw.w);
;                     }
;                     u32x4 w; w.x = cvt_pk_bf16(o[0], o[1]); w.y = cvt_pk_bf16(o[2], o[3]); w.z = cvt_pk_bf16(o[4], o[5]); w.w = cvt_pk_bf16(o[6], o[7]);
;                     if (isA) *(u32x4*)(OMA + off + bj * HALF) = w; else *(u32x4*)(GI + off + bj * HALF) = w; } }
.LBB0_359:
	v_pk_add_f32 v[104:105], v[104:105], v[32:33]
	v_pk_add_f32 v[102:103], v[102:103], v[30:31]
	v_pk_add_f32 v[100:101], v[100:101], v[28:29]
	v_pk_add_f32 v[98:99], v[98:99], v[26:27]
	v_cvt_pk_bf16_f32 v118, v108, v109
	v_cvt_pk_bf16_f32 v119, v110, v111
	v_cvt_pk_bf16_f32 v120, v112, v113
	v_cvt_pk_bf16_f32 v121, v116, v117
	v_lshl_add_u64 v[108:109], v[114:115], 1, s[44:45]
	s_mov_b64 s[10:11], -1
	s_and_b64 vcc, exec, s[40:41]
	v_mul_f32_e32 v117, 0xbfb8aa3b, v102
	v_mul_f32_e32 v115, 0xbfb8aa3b, v103
	v_mul_f32_e32 v113, 0xbfb8aa3b, v104
	v_mul_f32_e32 v111, 0xbfb8aa3b, v105
	v_mul_f32_e32 v116, 0xbfb8aa3b, v98
	v_mul_f32_e32 v114, 0xbfb8aa3b, v99
	v_mul_f32_e32 v112, 0xbfb8aa3b, v100
	v_mul_f32_e32 v110, 0xbfb8aa3b, v101
	global_store_dwordx4 v[108:109], v[118:121], off
	s_cbranch_vccnz .LBB0_361
	s_nop 0
	v_exp_f32_e32 v98, v117
	v_exp_f32_e32 v99, v115
	s_mov_b64 s[10:11], 0
	v_add_f32_e32 v98, 1.0, v98
	v_add_f32_e32 v99, 1.0, v99
	v_rcp_f32_e32 v98, v98
	v_rcp_f32_e32 v99, v99
	s_waitcnt vmcnt(2)
	v_mov_b64_e32 v[102:103], v[232:233]
	v_mov_b64_e32 v[104:105], v[234:235]
	v_lshlrev_b32_e32 v100, 16, v102
	v_and_b32_e32 v101, 0xffff0000, v102
	v_pk_mul_f32 v[98:99], v[98:99], v[100:101]
	v_exp_f32_e32 v100, v113
	v_exp_f32_e32 v101, v111
	v_lshlrev_b32_e32 v102, 16, v103
	v_and_b32_e32 v103, 0xffff0000, v103
	v_add_f32_e32 v100, 1.0, v100
	v_add_f32_e32 v101, 1.0, v101
	v_rcp_f32_e32 v100, v100
	v_rcp_f32_e32 v101, v101
	v_lshlrev_b32_e32 v106, 16, v104
	v_and_b32_e32 v107, 0xffff0000, v104
	v_exp_f32_e32 v104, v112
	v_pk_mul_f32 v[100:101], v[100:101], v[102:103]
	v_exp_f32_e32 v102, v116
	v_exp_f32_e32 v103, v114
	v_add_f32_e32 v104, 1.0, v104
	v_add_f32_e32 v102, 1.0, v102
	v_add_f32_e32 v103, 1.0, v103
	v_rcp_f32_e32 v102, v102
	v_rcp_f32_e32 v103, v103
	s_nop 0
	v_pk_mul_f32 v[102:103], v[102:103], v[106:107]
	v_rcp_f32_e32 v106, v104
	v_exp_f32_e32 v104, v110
	s_nop 0
	v_add_f32_e32 v104, 1.0, v104
	v_rcp_f32_e32 v107, v104
	v_lshlrev_b32_e32 v104, 16, v105
	v_and_b32_e32 v105, 0xffff0000, v105
	v_pk_mul_f32 v[104:105], v[106:107], v[104:105]

; __device__ __forceinline__ unsigned cvt_pk_bf16(float lo, float hi) { unsigned r; asm volatile("v_cvt_pk_bf16_f32 %0, %1, %2" : "=v"(r) : "v"(lo), "v"(hi)); return r; }
; __device__ __forceinline__ float sigmoid_f(float x) { return __builtin_amdgcn_rcpf(1.0f + __builtin_amdgcn_exp2f(-1.4426950409f * x)); }
; __device__ __forceinline__ float bf_lo(unsigned w) { return __uint_as_float(w << 16); }
; __device__ __forceinline__ float bf_hi(unsigned w) { return __uint_as_float(w & 0xffff0000u); }
;     __device__ __forceinline__ void operator()(const f32x4 (&acc)[2][2][4][2], const Unit& u, int wr, int wc, int fr, int fq) const {
;     ...
;             for (int m = 0; m < 4; ++m) { const size_t off = (size_t)(row0 + ai * HALF + m * 16) * 2048 + col0;
; #pragma unroll
;                 for (int bj = 0; bj < 2; ++bj) { const f32x4 v0 = acc[ai][bj][m][0] + bv[bj][0], v1 = acc[ai][bj][m][1] + bv[bj][1]; float o[8];
;                     if (isA) {
; #pragma unroll
;                         for (int e = 0; e < 4; ++e) { o[e] = 1.0f - __builtin_amdgcn_exp2f(sigmoid_f(v0[e]) * sv[bj][0][e]); o[4 + e] = 1.0f - __builtin_amdgcn_exp2f(sigmoid_f(v1[e]) * sv[bj][1][e]); }
;                     } else {
;                         const u32x4 uw = *(const u32x4*)(UC + off + bj * HALF);
;                         o[0] = sigmoid_f(v0[0]) * bf_lo(uw.x); o[1] = sigmoid_f(v0[1]) * bf_hi(uw.x); o[2] = sigmoid_f(v0[2]) * bf_lo(uw.y); o[3] = sigmoid_f(v0[3]) * bf_hi(uw.y);
;                         o[4] = sigmoid_f(v1[0]) * bf_lo(uw.z); o[5] = sigmoid_f(v1[1]) * bf_hi(uw.z); o[6] = sigmoid_f(v1[2]) * bf_lo(uw.w); o[7] = sigmoid_f(v1[3]) * bf_hi(uw.w);
;                     }
;                     u32x4 w; w.x = cvt_pk_bf16(o[0], o[1]); w.y = cvt_pk_bf16(o[2], o[3]); w.z = cvt_pk_bf16(o[4], o[5]); w.w = cvt_pk_bf16(o[6], o[7]);
;                     if (isA) *(u32x4*)(OMA + off + bj * HALF) = w; else *(u32x4*)(GI + off + bj * HALF) = w; } }
.LBB0_363:
	v_cvt_pk_bf16_f32 v98, v98, v99
	v_cvt_pk_bf16_f32 v99, v100, v101
	v_cvt_pk_bf16_f32 v100, v102, v103
	v_cvt_pk_bf16_f32 v101, v104, v105
	global_store_dwordx4 v[108:109], v[98:101], off offset:256
	v_pk_add_f32 v[96:97], v[96:97], v[48:49]
	v_pk_add_f32 v[94:95], v[94:95], v[46:47]
	v_or_b32_e32 v98, 48, v174
	v_ashrrev_i32_e32 v99, 31, v98
	v_lshlrev_b64 v[98:99], 11, v[98:99]
	v_lshl_add_u64 v[98:99], v[98:99], 0, v[172:173]
	v_pk_add_f32 v[92:93], v[92:93], v[44:45]
	v_pk_add_f32 v[100:101], v[90:91], v[42:43]
	s_mov_b64 s[10:11], -1
	s_and_b64 vcc, exec, s[40:41]
	v_lshl_add_u64 v[90:91], v[98:99], 1, s[46:47]
	v_mul_f32_e32 v109, 0xbfb8aa3b, v94
	v_mul_f32_e32 v107, 0xbfb8aa3b, v95
	v_mul_f32_e32 v105, 0xbfb8aa3b, v96
	v_mul_f32_e32 v103, 0xbfb8aa3b, v97
	v_mul_f32_e32 v108, 0xbfb8aa3b, v100
	v_mul_f32_e32 v106, 0xbfb8aa3b, v101
	v_mul_f32_e32 v104, 0xbfb8aa3b, v92
	v_mul_f32_e32 v102, 0xbfb8aa3b, v93
	s_cbranch_vccnz .LBB0_365
	s_nop 0
	v_exp_f32_e32 v92, v109
	v_exp_f32_e32 v93, v107
	s_mov_b64 s[10:11], 0
	v_add_f32_e32 v92, 1.0, v92
	v_add_f32_e32 v93, 1.0, v93
	v_rcp_f32_e32 v92, v92
	v_rcp_f32_e32 v93, v93
	s_waitcnt vmcnt(1)
	v_mov_b64_e32 v[110:111], v[236:237]
	v_mov_b64_e32 v[112:113], v[238:239]
	v_lshlrev_b32_e32 v94, 16, v110
	v_and_b32_e32 v95, 0xffff0000, v110
	v_pk_mul_f32 v[92:93], v[92:93], v[94:95]
	v_exp_f32_e32 v94, v105
	v_exp_f32_e32 v95, v103
	v_lshlrev_b32_e32 v96, 16, v111
	v_and_b32_e32 v97, 0xffff0000, v111
	v_add_f32_e32 v94, 1.0, v94
	v_add_f32_e32 v95, 1.0, v95
	v_rcp_f32_e32 v94, v94
	v_rcp_f32_e32 v95, v95
	v_lshlrev_b32_e32 v100, 16, v112
	v_and_b32_e32 v101, 0xffff0000, v112
	v_lshlrev_b32_e32 v110, 16, v113
	v_pk_mul_f32 v[94:95], v[94:95], v[96:97]
	v_exp_f32_e32 v96, v108
	v_exp_f32_e32 v97, v106
	v_and_b32_e32 v111, 0xffff0000, v113
	v_add_f32_e32 v96, 1.0, v96
	v_add_f32_e32 v97, 1.0, v97
	v_rcp_f32_e32 v96, v96
	v_rcp_f32_e32 v97, v97
	s_nop 0
	v_pk_mul_f32 v[96:97], v[96:97], v[100:101]
	v_exp_f32_e32 v100, v104
	v_exp_f32_e32 v101, v102
	v_add_f32_e32 v100, 1.0, v100
	v_add_f32_e32 v101, 1.0, v101
	v_rcp_f32_e32 v100, v100
	v_rcp_f32_e32 v101, v101
	s_nop 0
	v_pk_mul_f32 v[100:101], v[100:101], v[110:111]

; __device__ __forceinline__ unsigned cvt_pk_bf16(float lo, float hi) { unsigned r; asm volatile("v_cvt_pk_bf16_f32 %0, %1, %2" : "=v"(r) : "v"(lo), "v"(hi)); return r; }
; __device__ __forceinline__ float sigmoid_f(float x) { return __builtin_amdgcn_rcpf(1.0f + __builtin_amdgcn_exp2f(-1.4426950409f * x)); }
; __device__ __forceinline__ float bf_lo(unsigned w) { return __uint_as_float(w << 16); }
; __device__ __forceinline__ float bf_hi(unsigned w) { return __uint_as_float(w & 0xffff0000u); }
;     __device__ __forceinline__ void operator()(const f32x4 (&acc)[2][2][4][2], const Unit& u, int wr, int wc, int fr, int fq) const {
;     ...
;             for (int m = 0; m < 4; ++m) { const size_t off = (size_t)(row0 + ai * HALF + m * 16) * 2048 + col0;
; #pragma unroll
;                 for (int bj = 0; bj < 2; ++bj) { const f32x4 v0 = acc[ai][bj][m][0] + bv[bj][0], v1 = acc[ai][bj][m][1] + bv[bj][1]; float o[8];
;                     if (isA) {
; #pragma unroll
;                         for (int e = 0; e < 4; ++e) { o[e] = 1.0f - __builtin_amdgcn_exp2f(sigmoid_f(v0[e]) * sv[bj][0][e]); o[4 + e] = 1.0f - __builtin_amdgcn_exp2f(sigmoid_f(v1[e]) * sv[bj][1][e]); }
;                     } else {
;                         const u32x4 uw = *(const u32x4*)(UC + off + bj * HALF);
;                         o[0] = sigmoid_f(v0[0]) * bf_lo(uw.x); o[1] = sigmoid_f(v0[1]) * bf_hi(uw.x); o[2] = sigmoid_f(v0[2]) * bf_lo(uw.y); o[3] = sigmoid_f(v0[3]) * bf_hi(uw.y);
;                         o[4] = sigmoid_f(v1[0]) * bf_lo(uw.z); o[5] = sigmoid_f(v1[1]) * bf_hi(uw.z); o[6] = sigmoid_f(v1[2]) * bf_lo(uw.w); o[7] = sigmoid_f(v1[3]) * bf_hi(uw.w);
;                     }
;                     u32x4 w; w.x = cvt_pk_bf16(o[0], o[1]); w.y = cvt_pk_bf16(o[2], o[3]); w.z = cvt_pk_bf16(o[4], o[5]); w.w = cvt_pk_bf16(o[6], o[7]);
;                     if (isA) *(u32x4*)(OMA + off + bj * HALF) = w; else *(u32x4*)(GI + off + bj * HALF) = w; } }
.LBB0_367:
	v_pk_add_f32 v[88:89], v[88:89], v[32:33]
	v_pk_add_f32 v[86:87], v[86:87], v[30:31]
	v_pk_add_f32 v[84:85], v[84:85], v[28:29]
	v_pk_add_f32 v[82:83], v[82:83], v[26:27]
	v_cvt_pk_bf16_f32 v102, v92, v93
	v_cvt_pk_bf16_f32 v103, v94, v95
	v_cvt_pk_bf16_f32 v104, v96, v97
	v_cvt_pk_bf16_f32 v105, v100, v101
	v_lshl_add_u64 v[92:93], v[98:99], 1, s[44:45]
	s_mov_b64 s[10:11], -1
	s_and_b64 vcc, exec, s[40:41]
	v_mul_f32_e32 v101, 0xbfb8aa3b, v86
	v_mul_f32_e32 v99, 0xbfb8aa3b, v87
	v_mul_f32_e32 v97, 0xbfb8aa3b, v88
	v_mul_f32_e32 v95, 0xbfb8aa3b, v89
	v_mul_f32_e32 v100, 0xbfb8aa3b, v82
	v_mul_f32_e32 v98, 0xbfb8aa3b, v83
	v_mul_f32_e32 v96, 0xbfb8aa3b, v84
	v_mul_f32_e32 v94, 0xbfb8aa3b, v85
	global_store_dwordx4 v[92:93], v[102:105], off
	s_cbranch_vccnz .LBB0_369
	s_nop 0
	v_exp_f32_e32 v82, v101
	v_exp_f32_e32 v83, v99
	s_mov_b64 s[10:11], 0
	v_add_f32_e32 v82, 1.0, v82
	v_add_f32_e32 v83, 1.0, v83
	v_rcp_f32_e32 v82, v82
	v_rcp_f32_e32 v83, v83
	s_waitcnt vmcnt(0)
	v_mov_b64_e32 v[86:87], v[240:241]
	v_mov_b64_e32 v[88:89], v[242:243]
	v_mov_b32_e32 v248, 0x80000
	v_mov_b32_e32 v249, 0
	v_lshl_add_u64 v[244:245], v[178:179], 0, v[248:249]
	global_load_dwordx4 v[190:193], v[244:245], off
	global_load_dwordx4 v[208:211], v[244:245], off offset:256
	v_mov_b32_e32 v248, 0x90000
	v_mov_b32_e32 v249, 0
	v_lshl_add_u64 v[246:247], v[178:179], 0, v[248:249]
	global_load_dwordx4 v[212:215], v[246:247], off
	global_load_dwordx4 v[216:219], v[246:247], off offset:256
	v_mov_b32_e32 v248, 0xa0000
	v_mov_b32_e32 v249, 0
	v_lshl_add_u64 v[244:245], v[178:179], 0, v[248:249]
	global_load_dwordx4 v[228:231], v[244:245], off
	global_load_dwordx4 v[232:235], v[244:245], off offset:256
	v_mov_b32_e32 v248, 0xb0000
	v_mov_b32_e32 v249, 0
	v_lshl_add_u64 v[246:247], v[178:179], 0, v[248:249]
	global_load_dwordx4 v[236:239], v[246:247], off
	global_load_dwordx4 v[240:243], v[246:247], off offset:256
	v_lshlrev_b32_e32 v84, 16, v86
	v_and_b32_e32 v85, 0xffff0000, v86
	v_pk_mul_f32 v[82:83], v[82:83], v[84:85]
	v_exp_f32_e32 v84, v97
	v_exp_f32_e32 v85, v95
	v_lshlrev_b32_e32 v86, 16, v87
	v_and_b32_e32 v87, 0xffff0000, v87
	v_add_f32_e32 v84, 1.0, v84
	v_add_f32_e32 v85, 1.0, v85
	v_rcp_f32_e32 v84, v84
	v_rcp_f32_e32 v85, v85
	v_lshlrev_b32_e32 v90, 16, v88
	v_and_b32_e32 v91, 0xffff0000, v88
	v_exp_f32_e32 v88, v96
	v_pk_mul_f32 v[84:85], v[84:85], v[86:87]
	v_exp_f32_e32 v86, v100
	v_exp_f32_e32 v87, v98
	v_add_f32_e32 v88, 1.0, v88
	v_add_f32_e32 v86, 1.0, v86
	v_add_f32_e32 v87, 1.0, v87
	v_rcp_f32_e32 v86, v86
	v_rcp_f32_e32 v87, v87
	s_nop 0
	v_pk_mul_f32 v[86:87], v[86:87], v[90:91]
	v_rcp_f32_e32 v90, v88
	v_exp_f32_e32 v88, v94
	s_nop 0
	v_add_f32_e32 v88, 1.0, v88
	v_rcp_f32_e32 v91, v88
	v_lshlrev_b32_e32 v88, 16, v89
	v_and_b32_e32 v89, 0xffff0000, v89
	v_pk_mul_f32 v[88:89], v[90:91], v[88:89]

; __device__ __forceinline__ unsigned cvt_pk_bf16(float lo, float hi) { unsigned r; asm volatile("v_cvt_pk_bf16_f32 %0, %1, %2" : "=v"(r) : "v"(lo), "v"(hi)); return r; }
; __device__ __forceinline__ float sigmoid_f(float x) { return __builtin_amdgcn_rcpf(1.0f + __builtin_amdgcn_exp2f(-1.4426950409f * x)); }
; __device__ __forceinline__ float bf_lo(unsigned w) { return __uint_as_float(w << 16); }
; __device__ __forceinline__ float bf_hi(unsigned w) { return __uint_as_float(w & 0xffff0000u); }
;     __device__ __forceinline__ void operator()(const f32x4 (&acc)[2][2][4][2], const Unit& u, int wr, int wc, int fr, int fq) const {
;     ...
;             for (int m = 0; m < 4; ++m) { const size_t off = (size_t)(row0 + ai * HALF + m * 16) * 2048 + col0;
; #pragma unroll
;                 for (int bj = 0; bj < 2; ++bj) { const f32x4 v0 = acc[ai][bj][m][0] + bv[bj][0], v1 = acc[ai][bj][m][1] + bv[bj][1]; float o[8];
;                     if (isA) {
; #pragma unroll
;                         for (int e = 0; e < 4; ++e) { o[e] = 1.0f - __builtin_amdgcn_exp2f(sigmoid_f(v0[e]) * sv[bj][0][e]); o[4 + e] = 1.0f - __builtin_amdgcn_exp2f(sigmoid_f(v1[e]) * sv[bj][1][e]); }
;                     } else {
;                         const u32x4 uw = *(const u32x4*)(UC + off + bj * HALF);
;                         o[0] = sigmoid_f(v0[0]) * bf_lo(uw.x); o[1] = sigmoid_f(v0[1]) * bf_hi(uw.x); o[2] = sigmoid_f(v0[2]) * bf_lo(uw.y); o[3] = sigmoid_f(v0[3]) * bf_hi(uw.y);
;                         o[4] = sigmoid_f(v1[0]) * bf_lo(uw.z); o[5] = sigmoid_f(v1[1]) * bf_hi(uw.z); o[6] = sigmoid_f(v1[2]) * bf_lo(uw.w); o[7] = sigmoid_f(v1[3]) * bf_hi(uw.w);
;                     }
;                     u32x4 w; w.x = cvt_pk_bf16(o[0], o[1]); w.y = cvt_pk_bf16(o[2], o[3]); w.z = cvt_pk_bf16(o[4], o[5]); w.w = cvt_pk_bf16(o[6], o[7]);
;                     if (isA) *(u32x4*)(OMA + off + bj * HALF) = w; else *(u32x4*)(GI + off + bj * HALF) = w; } }
.LBB0_371:
	v_cvt_pk_bf16_f32 v82, v82, v83
	v_cvt_pk_bf16_f32 v83, v84, v85
	v_cvt_pk_bf16_f32 v84, v86, v87
	v_cvt_pk_bf16_f32 v85, v88, v89
	global_store_dwordx4 v[92:93], v[82:85], off offset:256
	s_mov_b64 s[10:11], 0x40000
	v_pk_add_f32 v[80:81], v[80:81], v[48:49]
	v_lshlrev_b64 v[82:83], 11, v[174:175]
	v_lshl_add_u64 v[82:83], v[82:83], 0, v[172:173]
	v_lshl_add_u64 v[82:83], v[82:83], 0, s[10:11]
	v_pk_add_f32 v[78:79], v[78:79], v[46:47]
	v_pk_add_f32 v[76:77], v[76:77], v[44:45]
	v_pk_add_f32 v[84:85], v[74:75], v[42:43]
	s_mov_b64 s[10:11], -1
	s_and_b64 vcc, exec, s[40:41]
	v_lshl_add_u64 v[74:75], v[82:83], 1, s[46:47]
	v_mul_f32_e32 v93, 0xbfb8aa3b, v78
	v_mul_f32_e32 v91, 0xbfb8aa3b, v79
	v_mul_f32_e32 v89, 0xbfb8aa3b, v80
	v_mul_f32_e32 v87, 0xbfb8aa3b, v81
	v_mul_f32_e32 v92, 0xbfb8aa3b, v84
	v_mul_f32_e32 v90, 0xbfb8aa3b, v85
	v_mul_f32_e32 v88, 0xbfb8aa3b, v76
	v_mul_f32_e32 v86, 0xbfb8aa3b, v77
	s_cbranch_vccnz .LBB0_373
	s_nop 0
	v_exp_f32_e32 v76, v93
	v_exp_f32_e32 v77, v91
	s_mov_b64 s[10:11], 0
	v_add_f32_e32 v76, 1.0, v76
	v_add_f32_e32 v77, 1.0, v77
	v_rcp_f32_e32 v76, v76
	v_rcp_f32_e32 v77, v77
	s_waitcnt vmcnt(7)
	v_mov_b64_e32 v[94:95], v[190:191]
	v_mov_b64_e32 v[96:97], v[192:193]
	v_lshlrev_b32_e32 v78, 16, v94
	v_and_b32_e32 v79, 0xffff0000, v94
	v_pk_mul_f32 v[76:77], v[76:77], v[78:79]
	v_exp_f32_e32 v78, v89
	v_exp_f32_e32 v79, v87
	v_lshlrev_b32_e32 v80, 16, v95
	v_and_b32_e32 v81, 0xffff0000, v95
	v_add_f32_e32 v78, 1.0, v78
	v_add_f32_e32 v79, 1.0, v79
	v_rcp_f32_e32 v78, v78
	v_rcp_f32_e32 v79, v79
	v_lshlrev_b32_e32 v84, 16, v96
	v_and_b32_e32 v85, 0xffff0000, v96
	v_lshlrev_b32_e32 v94, 16, v97
	v_pk_mul_f32 v[78:79], v[78:79], v[80:81]
	v_exp_f32_e32 v80, v92
	v_exp_f32_e32 v81, v90
	v_and_b32_e32 v95, 0xffff0000, v97
	v_add_f32_e32 v80, 1.0, v80
	v_add_f32_e32 v81, 1.0, v81
	v_rcp_f32_e32 v80, v80
	v_rcp_f32_e32 v81, v81
	s_nop 0
	v_pk_mul_f32 v[80:81], v[80:81], v[84:85]
	v_exp_f32_e32 v84, v88
	v_exp_f32_e32 v85, v86
	v_add_f32_e32 v84, 1.0, v84
	v_add_f32_e32 v85, 1.0, v85
	v_rcp_f32_e32 v84, v84
	v_rcp_f32_e32 v85, v85
	s_nop 0
	v_pk_mul_f32 v[84:85], v[84:85], v[94:95]

; __device__ __forceinline__ unsigned cvt_pk_bf16(float lo, float hi) { unsigned r; asm volatile("v_cvt_pk_bf16_f32 %0, %1, %2" : "=v"(r) : "v"(lo), "v"(hi)); return r; }
; __device__ __forceinline__ float sigmoid_f(float x) { return __builtin_amdgcn_rcpf(1.0f + __builtin_amdgcn_exp2f(-1.4426950409f * x)); }
; __device__ __forceinline__ float bf_lo(unsigned w) { return __uint_as_float(w << 16); }
; __device__ __forceinline__ float bf_hi(unsigned w) { return __uint_as_float(w & 0xffff0000u); }
;     __device__ __forceinline__ void operator()(const f32x4 (&acc)[2][2][4][2], const Unit& u, int wr, int wc, int fr, int fq) const {
;     ...
;             for (int m = 0; m < 4; ++m) { const size_t off = (size_t)(row0 + ai * HALF + m * 16) * 2048 + col0;
; #pragma unroll
;                 for (int bj = 0; bj < 2; ++bj) { const f32x4 v0 = acc[ai][bj][m][0] + bv[bj][0], v1 = acc[ai][bj][m][1] + bv[bj][1]; float o[8];
;                     if (isA) {
; #pragma unroll
;                         for (int e = 0; e < 4; ++e) { o[e] = 1.0f - __builtin_amdgcn_exp2f(sigmoid_f(v0[e]) * sv[bj][0][e]); o[4 + e] = 1.0f - __builtin_amdgcn_exp2f(sigmoid_f(v1[e]) * sv[bj][1][e]); }
;                     } else {
;                         const u32x4 uw = *(const u32x4*)(UC + off + bj * HALF);
;                         o[0] = sigmoid_f(v0[0]) * bf_lo(uw.x); o[1] = sigmoid_f(v0[1]) * bf_hi(uw.x); o[2] = sigmoid_f(v0[2]) * bf_lo(uw.y); o[3] = sigmoid_f(v0[3]) * bf_hi(uw.y);
;                         o[4] = sigmoid_f(v1[0]) * bf_lo(uw.z); o[5] = sigmoid_f(v1[1]) * bf_hi(uw.z); o[6] = sigmoid_f(v1[2]) * bf_lo(uw.w); o[7] = sigmoid_f(v1[3]) * bf_hi(uw.w);
;                     }
;                     u32x4 w; w.x = cvt_pk_bf16(o[0], o[1]); w.y = cvt_pk_bf16(o[2], o[3]); w.z = cvt_pk_bf16(o[4], o[5]); w.w = cvt_pk_bf16(o[6], o[7]);
;                     if (isA) *(u32x4*)(OMA + off + bj * HALF) = w; else *(u32x4*)(GI + off + bj * HALF) = w; } }
.LBB0_375:
	v_pk_add_f32 v[72:73], v[72:73], v[32:33]
	v_pk_add_f32 v[70:71], v[70:71], v[30:31]
	v_pk_add_f32 v[68:69], v[68:69], v[28:29]
	v_pk_add_f32 v[66:67], v[66:67], v[26:27]
	v_cvt_pk_bf16_f32 v86, v76, v77
	v_cvt_pk_bf16_f32 v87, v78, v79
	v_cvt_pk_bf16_f32 v88, v80, v81
	v_cvt_pk_bf16_f32 v89, v84, v85
	v_lshl_add_u64 v[76:77], v[82:83], 1, s[44:45]
	s_mov_b64 s[10:11], -1
	s_and_b64 vcc, exec, s[40:41]
	v_mul_f32_e32 v85, 0xbfb8aa3b, v70
	v_mul_f32_e32 v83, 0xbfb8aa3b, v71
	v_mul_f32_e32 v81, 0xbfb8aa3b, v72
	v_mul_f32_e32 v79, 0xbfb8aa3b, v73
	v_mul_f32_e32 v84, 0xbfb8aa3b, v66
	v_mul_f32_e32 v82, 0xbfb8aa3b, v67
	v_mul_f32_e32 v80, 0xbfb8aa3b, v68
	v_mul_f32_e32 v78, 0xbfb8aa3b, v69
	global_store_dwordx4 v[76:77], v[86:89], off
	s_cbranch_vccnz .LBB0_377
	s_nop 0
	v_exp_f32_e32 v66, v85
	v_exp_f32_e32 v67, v83
	s_mov_b64 s[10:11], 0
	v_add_f32_e32 v66, 1.0, v66
	v_add_f32_e32 v67, 1.0, v67
	v_rcp_f32_e32 v66, v66
	v_rcp_f32_e32 v67, v67
	s_waitcnt vmcnt(6)
	v_mov_b64_e32 v[70:71], v[208:209]
	v_mov_b64_e32 v[72:73], v[210:211]
	v_lshlrev_b32_e32 v68, 16, v70
	v_and_b32_e32 v69, 0xffff0000, v70
	v_pk_mul_f32 v[66:67], v[66:67], v[68:69]
	v_exp_f32_e32 v68, v81
	v_exp_f32_e32 v69, v79
	v_lshlrev_b32_e32 v70, 16, v71
	v_and_b32_e32 v71, 0xffff0000, v71
	v_add_f32_e32 v68, 1.0, v68
	v_add_f32_e32 v69, 1.0, v69
	v_rcp_f32_e32 v68, v68
	v_rcp_f32_e32 v69, v69
	v_lshlrev_b32_e32 v74, 16, v72
	v_and_b32_e32 v75, 0xffff0000, v72
	v_exp_f32_e32 v72, v80
	v_pk_mul_f32 v[68:69], v[68:69], v[70:71]
	v_exp_f32_e32 v70, v84
	v_exp_f32_e32 v71, v82
	v_add_f32_e32 v72, 1.0, v72
	v_add_f32_e32 v70, 1.0, v70
	v_add_f32_e32 v71, 1.0, v71
	v_rcp_f32_e32 v70, v70
	v_rcp_f32_e32 v71, v71
	s_nop 0
	v_pk_mul_f32 v[70:71], v[70:71], v[74:75]
	v_rcp_f32_e32 v74, v72
	v_exp_f32_e32 v72, v78
	s_nop 0
	v_add_f32_e32 v72, 1.0, v72
	v_rcp_f32_e32 v75, v72
	v_lshlrev_b32_e32 v72, 16, v73
	v_and_b32_e32 v73, 0xffff0000, v73
	v_pk_mul_f32 v[72:73], v[74:75], v[72:73]

; __device__ __forceinline__ unsigned cvt_pk_bf16(float lo, float hi) { unsigned r; asm volatile("v_cvt_pk_bf16_f32 %0, %1, %2" : "=v"(r) : "v"(lo), "v"(hi)); return r; }
; __device__ __forceinline__ float sigmoid_f(float x) { return __builtin_amdgcn_rcpf(1.0f + __builtin_amdgcn_exp2f(-1.4426950409f * x)); }
; __device__ __forceinline__ float bf_lo(unsigned w) { return __uint_as_float(w << 16); }
; __device__ __forceinline__ float bf_hi(unsigned w) { return __uint_as_float(w & 0xffff0000u); }
;     __device__ __forceinline__ void operator()(const f32x4 (&acc)[2][2][4][2], const Unit& u, int wr, int wc, int fr, int fq) const {
;     ...
;             for (int m = 0; m < 4; ++m) { const size_t off = (size_t)(row0 + ai * HALF + m * 16) * 2048 + col0;
; #pragma unroll
;                 for (int bj = 0; bj < 2; ++bj) { const f32x4 v0 = acc[ai][bj][m][0] + bv[bj][0], v1 = acc[ai][bj][m][1] + bv[bj][1]; float o[8];
;                     if (isA) {
; #pragma unroll
;                         for (int e = 0; e < 4; ++e) { o[e] = 1.0f - __builtin_amdgcn_exp2f(sigmoid_f(v0[e]) * sv[bj][0][e]); o[4 + e] = 1.0f - __builtin_amdgcn_exp2f(sigmoid_f(v1[e]) * sv[bj][1][e]); }
;                     } else {
;                         const u32x4 uw = *(const u32x4*)(UC + off + bj * HALF);
;                         o[0] = sigmoid_f(v0[0]) * bf_lo(uw.x); o[1] = sigmoid_f(v0[1]) * bf_hi(uw.x); o[2] = sigmoid_f(v0[2]) * bf_lo(uw.y); o[3] = sigmoid_f(v0[3]) * bf_hi(uw.y);
;                         o[4] = sigmoid_f(v1[0]) * bf_lo(uw.z); o[5] = sigmoid_f(v1[1]) * bf_hi(uw.z); o[6] = sigmoid_f(v1[2]) * bf_lo(uw.w); o[7] = sigmoid_f(v1[3]) * bf_hi(uw.w);
;                     }
;                     u32x4 w; w.x = cvt_pk_bf16(o[0], o[1]); w.y = cvt_pk_bf16(o[2], o[3]); w.z = cvt_pk_bf16(o[4], o[5]); w.w = cvt_pk_bf16(o[6], o[7]);
;                     if (isA) *(u32x4*)(OMA + off + bj * HALF) = w; else *(u32x4*)(GI + off + bj * HALF) = w; } }
.LBB0_379:
	v_cvt_pk_bf16_f32 v66, v66, v67
	v_cvt_pk_bf16_f32 v67, v68, v69
	v_cvt_pk_bf16_f32 v68, v70, v71
	v_cvt_pk_bf16_f32 v69, v72, v73
	global_store_dwordx4 v[76:77], v[66:69], off offset:256
	s_mov_b64 s[10:11], 0x48000
	v_pk_add_f32 v[64:65], v[64:65], v[48:49]
	v_lshlrev_b64 v[66:67], 11, v[174:175]
	v_lshl_add_u64 v[66:67], v[66:67], 0, v[172:173]
	v_lshl_add_u64 v[66:67], v[66:67], 0, s[10:11]
	v_pk_add_f32 v[62:63], v[62:63], v[46:47]
	v_pk_add_f32 v[60:61], v[60:61], v[44:45]
	v_pk_add_f32 v[68:69], v[58:59], v[42:43]
	s_mov_b64 s[10:11], -1
	s_and_b64 vcc, exec, s[40:41]
	v_lshl_add_u64 v[58:59], v[66:67], 1, s[46:47]
	v_mul_f32_e32 v77, 0xbfb8aa3b, v62
	v_mul_f32_e32 v75, 0xbfb8aa3b, v63
	v_mul_f32_e32 v73, 0xbfb8aa3b, v64
	v_mul_f32_e32 v71, 0xbfb8aa3b, v65
	v_mul_f32_e32 v76, 0xbfb8aa3b, v68
	v_mul_f32_e32 v74, 0xbfb8aa3b, v69
	v_mul_f32_e32 v72, 0xbfb8aa3b, v60
	v_mul_f32_e32 v70, 0xbfb8aa3b, v61
	s_cbranch_vccnz .LBB0_381
	s_nop 0
	v_exp_f32_e32 v60, v77
	v_exp_f32_e32 v61, v75
	s_mov_b64 s[10:11], 0
	v_add_f32_e32 v60, 1.0, v60
	v_add_f32_e32 v61, 1.0, v61
	v_rcp_f32_e32 v60, v60
	v_rcp_f32_e32 v61, v61
	s_waitcnt vmcnt(5)
	v_mov_b64_e32 v[78:79], v[212:213]
	v_mov_b64_e32 v[80:81], v[214:215]
	v_lshlrev_b32_e32 v62, 16, v78
	v_and_b32_e32 v63, 0xffff0000, v78
	v_pk_mul_f32 v[60:61], v[60:61], v[62:63]
	v_exp_f32_e32 v62, v73
	v_exp_f32_e32 v63, v71
	v_lshlrev_b32_e32 v64, 16, v79
	v_and_b32_e32 v65, 0xffff0000, v79
	v_add_f32_e32 v62, 1.0, v62
	v_add_f32_e32 v63, 1.0, v63
	v_rcp_f32_e32 v62, v62
	v_rcp_f32_e32 v63, v63
	v_lshlrev_b32_e32 v68, 16, v80
	v_and_b32_e32 v69, 0xffff0000, v80
	v_lshlrev_b32_e32 v78, 16, v81
	v_pk_mul_f32 v[62:63], v[62:63], v[64:65]
	v_exp_f32_e32 v64, v76
	v_exp_f32_e32 v65, v74
	v_and_b32_e32 v79, 0xffff0000, v81
	v_add_f32_e32 v64, 1.0, v64
	v_add_f32_e32 v65, 1.0, v65
	v_rcp_f32_e32 v64, v64
	v_rcp_f32_e32 v65, v65
	s_nop 0
	v_pk_mul_f32 v[64:65], v[64:65], v[68:69]
	v_exp_f32_e32 v68, v72
	v_exp_f32_e32 v69, v70
	v_add_f32_e32 v68, 1.0, v68
	v_add_f32_e32 v69, 1.0, v69
	v_rcp_f32_e32 v68, v68
	v_rcp_f32_e32 v69, v69
	s_nop 0
	v_pk_mul_f32 v[68:69], v[68:69], v[78:79]

; __device__ __forceinline__ unsigned cvt_pk_bf16(float lo, float hi) { unsigned r; asm volatile("v_cvt_pk_bf16_f32 %0, %1, %2" : "=v"(r) : "v"(lo), "v"(hi)); return r; }
; __device__ __forceinline__ float sigmoid_f(float x) { return __builtin_amdgcn_rcpf(1.0f + __builtin_amdgcn_exp2f(-1.4426950409f * x)); }
; __device__ __forceinline__ float bf_lo(unsigned w) { return __uint_as_float(w << 16); }
; __device__ __forceinline__ float bf_hi(unsigned w) { return __uint_as_float(w & 0xffff0000u); }
;     __device__ __forceinline__ void operator()(const f32x4 (&acc)[2][2][4][2], const Unit& u, int wr, int wc, int fr, int fq) const {
;     ...
;             for (int m = 0; m < 4; ++m) { const size_t off = (size_t)(row0 + ai * HALF + m * 16) * 2048 + col0;
; #pragma unroll
;                 for (int bj = 0; bj < 2; ++bj) { const f32x4 v0 = acc[ai][bj][m][0] + bv[bj][0], v1 = acc[ai][bj][m][1] + bv[bj][1]; float o[8];
;                     if (isA) {
; #pragma unroll
;                         for (int e = 0; e < 4; ++e) { o[e] = 1.0f - __builtin_amdgcn_exp2f(sigmoid_f(v0[e]) * sv[bj][0][e]); o[4 + e] = 1.0f - __builtin_amdgcn_exp2f(sigmoid_f(v1[e]) * sv[bj][1][e]); }
;                     } else {
;                         const u32x4 uw = *(const u32x4*)(UC + off + bj * HALF);
;                         o[0] = sigmoid_f(v0[0]) * bf_lo(uw.x); o[1] = sigmoid_f(v0[1]) * bf_hi(uw.x); o[2] = sigmoid_f(v0[2]) * bf_lo(uw.y); o[3] = sigmoid_f(v0[3]) * bf_hi(uw.y);
;                         o[4] = sigmoid_f(v1[0]) * bf_lo(uw.z); o[5] = sigmoid_f(v1[1]) * bf_hi(uw.z); o[6] = sigmoid_f(v1[2]) * bf_lo(uw.w); o[7] = sigmoid_f(v1[3]) * bf_hi(uw.w);
;                     }
;                     u32x4 w; w.x = cvt_pk_bf16(o[0], o[1]); w.y = cvt_pk_bf16(o[2], o[3]); w.z = cvt_pk_bf16(o[4], o[5]); w.w = cvt_pk_bf16(o[6], o[7]);
;                     if (isA) *(u32x4*)(OMA + off + bj * HALF) = w; else *(u32x4*)(GI + off + bj * HALF) = w; } }
.LBB0_383:
	v_pk_add_f32 v[56:57], v[56:57], v[32:33]
	v_pk_add_f32 v[54:55], v[54:55], v[30:31]
	v_pk_add_f32 v[52:53], v[52:53], v[28:29]
	v_pk_add_f32 v[50:51], v[50:51], v[26:27]
	v_cvt_pk_bf16_f32 v70, v60, v61
	v_cvt_pk_bf16_f32 v71, v62, v63
	v_cvt_pk_bf16_f32 v72, v64, v65
	v_cvt_pk_bf16_f32 v73, v68, v69
	v_lshl_add_u64 v[60:61], v[66:67], 1, s[44:45]
	s_mov_b64 s[10:11], -1
	s_and_b64 vcc, exec, s[40:41]
	v_mul_f32_e32 v69, 0xbfb8aa3b, v54
	v_mul_f32_e32 v67, 0xbfb8aa3b, v55
	v_mul_f32_e32 v65, 0xbfb8aa3b, v56
	v_mul_f32_e32 v63, 0xbfb8aa3b, v57
	v_mul_f32_e32 v68, 0xbfb8aa3b, v50
	v_mul_f32_e32 v66, 0xbfb8aa3b, v51
	v_mul_f32_e32 v64, 0xbfb8aa3b, v52
	v_mul_f32_e32 v62, 0xbfb8aa3b, v53
	global_store_dwordx4 v[60:61], v[70:73], off
	s_cbranch_vccnz .LBB0_385
	s_nop 0
	v_exp_f32_e32 v50, v69
	v_exp_f32_e32 v51, v67
	s_mov_b64 s[10:11], 0
	v_add_f32_e32 v50, 1.0, v50
	v_add_f32_e32 v51, 1.0, v51
	v_rcp_f32_e32 v50, v50
	v_rcp_f32_e32 v51, v51
	s_waitcnt vmcnt(4)
	v_mov_b64_e32 v[54:55], v[216:217]
	v_mov_b64_e32 v[56:57], v[218:219]
	v_lshlrev_b32_e32 v52, 16, v54
	v_and_b32_e32 v53, 0xffff0000, v54
	v_pk_mul_f32 v[50:51], v[50:51], v[52:53]
	v_exp_f32_e32 v52, v65
	v_exp_f32_e32 v53, v63
	v_lshlrev_b32_e32 v54, 16, v55
	v_and_b32_e32 v55, 0xffff0000, v55
	v_add_f32_e32 v52, 1.0, v52
	v_add_f32_e32 v53, 1.0, v53
	v_rcp_f32_e32 v52, v52
	v_rcp_f32_e32 v53, v53
	v_lshlrev_b32_e32 v58, 16, v56
	v_and_b32_e32 v59, 0xffff0000, v56
	v_exp_f32_e32 v56, v64
	v_pk_mul_f32 v[52:53], v[52:53], v[54:55]
	v_exp_f32_e32 v54, v68
	v_exp_f32_e32 v55, v66
	v_add_f32_e32 v56, 1.0, v56
	v_add_f32_e32 v54, 1.0, v54
	v_add_f32_e32 v55, 1.0, v55
	v_rcp_f32_e32 v54, v54
	v_rcp_f32_e32 v55, v55
	s_nop 0
	v_pk_mul_f32 v[54:55], v[54:55], v[58:59]
	v_rcp_f32_e32 v58, v56
	v_exp_f32_e32 v56, v62
	s_nop 0
	v_add_f32_e32 v56, 1.0, v56
	v_rcp_f32_e32 v59, v56
	v_lshlrev_b32_e32 v56, 16, v57
	v_and_b32_e32 v57, 0xffff0000, v57
	v_pk_mul_f32 v[56:57], v[58:59], v[56:57]

; __device__ __forceinline__ unsigned cvt_pk_bf16(float lo, float hi) { unsigned r; asm volatile("v_cvt_pk_bf16_f32 %0, %1, %2" : "=v"(r) : "v"(lo), "v"(hi)); return r; }
; __device__ __forceinline__ float sigmoid_f(float x) { return __builtin_amdgcn_rcpf(1.0f + __builtin_amdgcn_exp2f(-1.4426950409f * x)); }
; __device__ __forceinline__ float bf_lo(unsigned w) { return __uint_as_float(w << 16); }
; __device__ __forceinline__ float bf_hi(unsigned w) { return __uint_as_float(w & 0xffff0000u); }
;     __device__ __forceinline__ void operator()(const f32x4 (&acc)[2][2][4][2], const Unit& u, int wr, int wc, int fr, int fq) const {
;     ...
;             for (int m = 0; m < 4; ++m) { const size_t off = (size_t)(row0 + ai * HALF + m * 16) * 2048 + col0;
; #pragma unroll
;                 for (int bj = 0; bj < 2; ++bj) { const f32x4 v0 = acc[ai][bj][m][0] + bv[bj][0], v1 = acc[ai][bj][m][1] + bv[bj][1]; float o[8];
;                     if (isA) {
; #pragma unroll
;                         for (int e = 0; e < 4; ++e) { o[e] = 1.0f - __builtin_amdgcn_exp2f(sigmoid_f(v0[e]) * sv[bj][0][e]); o[4 + e] = 1.0f - __builtin_amdgcn_exp2f(sigmoid_f(v1[e]) * sv[bj][1][e]); }
;                     } else {
;                         const u32x4 uw = *(const u32x4*)(UC + off + bj * HALF);
;                         o[0] = sigmoid_f(v0[0]) * bf_lo(uw.x); o[1] = sigmoid_f(v0[1]) * bf_hi(uw.x); o[2] = sigmoid_f(v0[2]) * bf_lo(uw.y); o[3] = sigmoid_f(v0[3]) * bf_hi(uw.y);
;                         o[4] = sigmoid_f(v1[0]) * bf_lo(uw.z); o[5] = sigmoid_f(v1[1]) * bf_hi(uw.z); o[6] = sigmoid_f(v1[2]) * bf_lo(uw.w); o[7] = sigmoid_f(v1[3]) * bf_hi(uw.w);
;                     }
;                     u32x4 w; w.x = cvt_pk_bf16(o[0], o[1]); w.y = cvt_pk_bf16(o[2], o[3]); w.z = cvt_pk_bf16(o[4], o[5]); w.w = cvt_pk_bf16(o[6], o[7]);
;                     if (isA) *(u32x4*)(OMA + off + bj * HALF) = w; else *(u32x4*)(GI + off + bj * HALF) = w; } }
.LBB0_387:
	v_cvt_pk_bf16_f32 v50, v50, v51
	v_cvt_pk_bf16_f32 v51, v52, v53
	v_cvt_pk_bf16_f32 v52, v54, v55
	v_cvt_pk_bf16_f32 v53, v56, v57
	global_store_dwordx4 v[60:61], v[50:53], off offset:256
	s_mov_b64 s[10:11], 0x50000
	v_pk_add_f32 v[40:41], v[40:41], v[48:49]
	v_lshlrev_b64 v[50:51], 11, v[174:175]
	v_lshl_add_u64 v[50:51], v[50:51], 0, v[172:173]
	v_lshl_add_u64 v[50:51], v[50:51], 0, s[10:11]
	v_pk_add_f32 v[38:39], v[38:39], v[46:47]
	v_pk_add_f32 v[36:37], v[36:37], v[44:45]
	v_pk_add_f32 v[52:53], v[34:35], v[42:43]
	s_mov_b64 s[10:11], -1
	s_and_b64 vcc, exec, s[40:41]
	v_lshl_add_u64 v[34:35], v[50:51], 1, s[46:47]
	v_mul_f32_e32 v61, 0xbfb8aa3b, v38
	v_mul_f32_e32 v59, 0xbfb8aa3b, v39
	v_mul_f32_e32 v57, 0xbfb8aa3b, v40
	v_mul_f32_e32 v55, 0xbfb8aa3b, v41
	v_mul_f32_e32 v60, 0xbfb8aa3b, v52
	v_mul_f32_e32 v58, 0xbfb8aa3b, v53
	v_mul_f32_e32 v56, 0xbfb8aa3b, v36
	v_mul_f32_e32 v54, 0xbfb8aa3b, v37
	s_cbranch_vccnz .LBB0_389
	s_nop 0
	v_exp_f32_e32 v36, v61
	v_exp_f32_e32 v37, v59
	s_mov_b64 s[10:11], 0
	v_add_f32_e32 v36, 1.0, v36
	v_add_f32_e32 v37, 1.0, v37
	v_rcp_f32_e32 v36, v36
	v_rcp_f32_e32 v37, v37
	s_waitcnt vmcnt(3)
	v_mov_b64_e32 v[62:63], v[228:229]
	v_mov_b64_e32 v[64:65], v[230:231]
	v_lshlrev_b32_e32 v38, 16, v62
	v_and_b32_e32 v39, 0xffff0000, v62
	v_pk_mul_f32 v[36:37], v[36:37], v[38:39]
	v_exp_f32_e32 v38, v57
	v_exp_f32_e32 v39, v55
	v_lshlrev_b32_e32 v40, 16, v63
	v_and_b32_e32 v41, 0xffff0000, v63
	v_add_f32_e32 v38, 1.0, v38
	v_add_f32_e32 v39, 1.0, v39
	v_rcp_f32_e32 v38, v38
	v_rcp_f32_e32 v39, v39
	v_lshlrev_b32_e32 v52, 16, v64
	v_and_b32_e32 v53, 0xffff0000, v64
	v_lshlrev_b32_e32 v62, 16, v65
	v_pk_mul_f32 v[38:39], v[38:39], v[40:41]
	v_exp_f32_e32 v40, v60
	v_exp_f32_e32 v41, v58
	v_and_b32_e32 v63, 0xffff0000, v65
	v_add_f32_e32 v40, 1.0, v40
	v_add_f32_e32 v41, 1.0, v41
	v_rcp_f32_e32 v40, v40
	v_rcp_f32_e32 v41, v41
	s_nop 0
	v_pk_mul_f32 v[40:41], v[40:41], v[52:53]
	v_exp_f32_e32 v52, v56
	v_exp_f32_e32 v53, v54
	v_add_f32_e32 v52, 1.0, v52
	v_add_f32_e32 v53, 1.0, v53
	v_rcp_f32_e32 v52, v52
	v_rcp_f32_e32 v53, v53
	s_nop 0
	v_pk_mul_f32 v[52:53], v[52:53], v[62:63]

; __device__ __forceinline__ unsigned cvt_pk_bf16(float lo, float hi) { unsigned r; asm volatile("v_cvt_pk_bf16_f32 %0, %1, %2" : "=v"(r) : "v"(lo), "v"(hi)); return r; }
; __device__ __forceinline__ float sigmoid_f(float x) { return __builtin_amdgcn_rcpf(1.0f + __builtin_amdgcn_exp2f(-1.4426950409f * x)); }
; __device__ __forceinline__ float bf_lo(unsigned w) { return __uint_as_float(w << 16); }
; __device__ __forceinline__ float bf_hi(unsigned w) { return __uint_as_float(w & 0xffff0000u); }
;     __device__ __forceinline__ void operator()(const f32x4 (&acc)[2][2][4][2], const Unit& u, int wr, int wc, int fr, int fq) const {
;     ...
;             for (int m = 0; m < 4; ++m) { const size_t off = (size_t)(row0 + ai * HALF + m * 16) * 2048 + col0;
; #pragma unroll
;                 for (int bj = 0; bj < 2; ++bj) { const f32x4 v0 = acc[ai][bj][m][0] + bv[bj][0], v1 = acc[ai][bj][m][1] + bv[bj][1]; float o[8];
;                     if (isA) {
; #pragma unroll
;                         for (int e = 0; e < 4; ++e) { o[e] = 1.0f - __builtin_amdgcn_exp2f(sigmoid_f(v0[e]) * sv[bj][0][e]); o[4 + e] = 1.0f - __builtin_amdgcn_exp2f(sigmoid_f(v1[e]) * sv[bj][1][e]); }
;                     } else {
;                         const u32x4 uw = *(const u32x4*)(UC + off + bj * HALF);
;                         o[0] = sigmoid_f(v0[0]) * bf_lo(uw.x); o[1] = sigmoid_f(v0[1]) * bf_hi(uw.x); o[2] = sigmoid_f(v0[2]) * bf_lo(uw.y); o[3] = sigmoid_f(v0[3]) * bf_hi(uw.y);
;                         o[4] = sigmoid_f(v1[0]) * bf_lo(uw.z); o[5] = sigmoid_f(v1[1]) * bf_hi(uw.z); o[6] = sigmoid_f(v1[2]) * bf_lo(uw.w); o[7] = sigmoid_f(v1[3]) * bf_hi(uw.w);
;                     }
;                     u32x4 w; w.x = cvt_pk_bf16(o[0], o[1]); w.y = cvt_pk_bf16(o[2], o[3]); w.z = cvt_pk_bf16(o[4], o[5]); w.w = cvt_pk_bf16(o[6], o[7]);
;                     if (isA) *(u32x4*)(OMA + off + bj * HALF) = w; else *(u32x4*)(GI + off + bj * HALF) = w; } }
.LBB0_391:
	v_pk_add_f32 v[24:25], v[24:25], v[32:33]
	v_pk_add_f32 v[22:23], v[22:23], v[30:31]
	v_pk_add_f32 v[20:21], v[20:21], v[28:29]
	v_pk_add_f32 v[18:19], v[18:19], v[26:27]
	v_cvt_pk_bf16_f32 v54, v36, v37
	v_cvt_pk_bf16_f32 v55, v38, v39
	v_cvt_pk_bf16_f32 v56, v40, v41
	v_cvt_pk_bf16_f32 v57, v52, v53
	v_lshl_add_u64 v[36:37], v[50:51], 1, s[44:45]
	s_mov_b64 s[10:11], -1
	s_and_b64 vcc, exec, s[40:41]
	v_mul_f32_e32 v53, 0xbfb8aa3b, v22
	v_mul_f32_e32 v51, 0xbfb8aa3b, v23
	v_mul_f32_e32 v41, 0xbfb8aa3b, v24
	v_mul_f32_e32 v39, 0xbfb8aa3b, v25
	v_mul_f32_e32 v52, 0xbfb8aa3b, v18
	v_mul_f32_e32 v50, 0xbfb8aa3b, v19
	v_mul_f32_e32 v40, 0xbfb8aa3b, v20
	v_mul_f32_e32 v38, 0xbfb8aa3b, v21
	global_store_dwordx4 v[36:37], v[54:57], off
	s_cbranch_vccnz .LBB0_393
	s_nop 0
	v_exp_f32_e32 v18, v53
	v_exp_f32_e32 v19, v51
	s_mov_b64 s[10:11], 0
	v_add_f32_e32 v18, 1.0, v18
	v_add_f32_e32 v19, 1.0, v19
	v_rcp_f32_e32 v18, v18
	v_rcp_f32_e32 v19, v19
	s_waitcnt vmcnt(2)
	v_mov_b64_e32 v[22:23], v[232:233]
	v_mov_b64_e32 v[24:25], v[234:235]
	v_lshlrev_b32_e32 v20, 16, v22
	v_and_b32_e32 v21, 0xffff0000, v22
	v_pk_mul_f32 v[18:19], v[18:19], v[20:21]
	v_exp_f32_e32 v20, v41
	v_exp_f32_e32 v21, v39
	v_lshlrev_b32_e32 v22, 16, v23
	v_and_b32_e32 v23, 0xffff0000, v23
	v_add_f32_e32 v20, 1.0, v20
	v_add_f32_e32 v21, 1.0, v21
	v_rcp_f32_e32 v20, v20
	v_rcp_f32_e32 v21, v21
	v_lshlrev_b32_e32 v34, 16, v24
	v_and_b32_e32 v35, 0xffff0000, v24
	v_exp_f32_e32 v24, v40
	v_pk_mul_f32 v[20:21], v[20:21], v[22:23]
	v_exp_f32_e32 v22, v52
	v_exp_f32_e32 v23, v50
	v_add_f32_e32 v24, 1.0, v24
	v_add_f32_e32 v22, 1.0, v22
	v_add_f32_e32 v23, 1.0, v23
	v_rcp_f32_e32 v22, v22
	v_rcp_f32_e32 v23, v23
	s_nop 0
	v_pk_mul_f32 v[22:23], v[22:23], v[34:35]
	v_rcp_f32_e32 v34, v24
	v_exp_f32_e32 v24, v38
	s_nop 0
	v_add_f32_e32 v24, 1.0, v24
	v_rcp_f32_e32 v35, v24
	v_lshlrev_b32_e32 v24, 16, v25
	v_and_b32_e32 v25, 0xffff0000, v25
	v_pk_mul_f32 v[24:25], v[34:35], v[24:25]

; __device__ __forceinline__ unsigned cvt_pk_bf16(float lo, float hi) { unsigned r; asm volatile("v_cvt_pk_bf16_f32 %0, %1, %2" : "=v"(r) : "v"(lo), "v"(hi)); return r; }
; __device__ __forceinline__ float sigmoid_f(float x) { return __builtin_amdgcn_rcpf(1.0f + __builtin_amdgcn_exp2f(-1.4426950409f * x)); }
; __device__ __forceinline__ float bf_lo(unsigned w) { return __uint_as_float(w << 16); }
; __device__ __forceinline__ float bf_hi(unsigned w) { return __uint_as_float(w & 0xffff0000u); }
;     __device__ __forceinline__ void operator()(const f32x4 (&acc)[2][2][4][2], const Unit& u, int wr, int wc, int fr, int fq) const {
;     ...
;             for (int m = 0; m < 4; ++m) { const size_t off = (size_t)(row0 + ai * HALF + m * 16) * 2048 + col0;
; #pragma unroll
;                 for (int bj = 0; bj < 2; ++bj) { const f32x4 v0 = acc[ai][bj][m][0] + bv[bj][0], v1 = acc[ai][bj][m][1] + bv[bj][1]; float o[8];
;                     if (isA) {
; #pragma unroll
;                         for (int e = 0; e < 4; ++e) { o[e] = 1.0f - __builtin_amdgcn_exp2f(sigmoid_f(v0[e]) * sv[bj][0][e]); o[4 + e] = 1.0f - __builtin_amdgcn_exp2f(sigmoid_f(v1[e]) * sv[bj][1][e]); }
;                     } else {
;                         const u32x4 uw = *(const u32x4*)(UC + off + bj * HALF);
;                         o[0] = sigmoid_f(v0[0]) * bf_lo(uw.x); o[1] = sigmoid_f(v0[1]) * bf_hi(uw.x); o[2] = sigmoid_f(v0[2]) * bf_lo(uw.y); o[3] = sigmoid_f(v0[3]) * bf_hi(uw.y);
;                         o[4] = sigmoid_f(v1[0]) * bf_lo(uw.z); o[5] = sigmoid_f(v1[1]) * bf_hi(uw.z); o[6] = sigmoid_f(v1[2]) * bf_lo(uw.w); o[7] = sigmoid_f(v1[3]) * bf_hi(uw.w);
;                     }
;                     u32x4 w; w.x = cvt_pk_bf16(o[0], o[1]); w.y = cvt_pk_bf16(o[2], o[3]); w.z = cvt_pk_bf16(o[4], o[5]); w.w = cvt_pk_bf16(o[6], o[7]);
;                     if (isA) *(u32x4*)(OMA + off + bj * HALF) = w; else *(u32x4*)(GI + off + bj * HALF) = w; } }
.LBB0_395:
	v_cvt_pk_bf16_f32 v18, v18, v19
	v_cvt_pk_bf16_f32 v19, v20, v21
	v_cvt_pk_bf16_f32 v20, v22, v23
	v_cvt_pk_bf16_f32 v21, v24, v25
	global_store_dwordx4 v[36:37], v[18:21], off offset:256
	s_mov_b64 s[10:11], 0x58000
	v_pk_add_f32 v[16:17], v[16:17], v[48:49]
	v_lshlrev_b64 v[18:19], 11, v[174:175]
	v_lshl_add_u64 v[18:19], v[18:19], 0, v[172:173]
	v_lshl_add_u64 v[18:19], v[18:19], 0, s[10:11]
	v_pk_add_f32 v[14:15], v[14:15], v[46:47]
	v_pk_add_f32 v[12:13], v[12:13], v[44:45]
	v_pk_add_f32 v[20:21], v[10:11], v[42:43]
	s_mov_b64 s[10:11], -1
	s_and_b64 vcc, exec, s[40:41]
	v_lshl_add_u64 v[10:11], v[18:19], 1, s[46:47]
	v_mul_f32_e32 v37, 0xbfb8aa3b, v14
	v_mul_f32_e32 v35, 0xbfb8aa3b, v15
	v_mul_f32_e32 v25, 0xbfb8aa3b, v16
	v_mul_f32_e32 v23, 0xbfb8aa3b, v17
	v_mul_f32_e32 v36, 0xbfb8aa3b, v20
	v_mul_f32_e32 v34, 0xbfb8aa3b, v21
	v_mul_f32_e32 v24, 0xbfb8aa3b, v12
	v_mul_f32_e32 v22, 0xbfb8aa3b, v13
	s_cbranch_vccnz .LBB0_397
	s_nop 0
	v_exp_f32_e32 v12, v37
	v_exp_f32_e32 v13, v35
	s_mov_b64 s[10:11], 0
	v_add_f32_e32 v12, 1.0, v12
	v_add_f32_e32 v13, 1.0, v13
	v_rcp_f32_e32 v12, v12
	v_rcp_f32_e32 v13, v13
	s_waitcnt vmcnt(1)
	v_mov_b64_e32 v[38:39], v[236:237]
	v_mov_b64_e32 v[40:41], v[238:239]
	v_lshlrev_b32_e32 v14, 16, v38
	v_and_b32_e32 v15, 0xffff0000, v38
	v_pk_mul_f32 v[12:13], v[12:13], v[14:15]
	v_exp_f32_e32 v14, v25
	v_exp_f32_e32 v15, v23
	v_lshlrev_b32_e32 v16, 16, v39
	v_and_b32_e32 v17, 0xffff0000, v39
	v_add_f32_e32 v14, 1.0, v14
	v_add_f32_e32 v15, 1.0, v15
	v_rcp_f32_e32 v14, v14
	v_rcp_f32_e32 v15, v15
	v_lshlrev_b32_e32 v20, 16, v40
	v_and_b32_e32 v21, 0xffff0000, v40
	v_lshlrev_b32_e32 v38, 16, v41
	v_pk_mul_f32 v[14:15], v[14:15], v[16:17]
	v_exp_f32_e32 v16, v36
	v_exp_f32_e32 v17, v34
	v_and_b32_e32 v39, 0xffff0000, v41
	v_add_f32_e32 v16, 1.0, v16
	v_add_f32_e32 v17, 1.0, v17
	v_rcp_f32_e32 v16, v16
	v_rcp_f32_e32 v17, v17
	s_nop 0
	v_pk_mul_f32 v[16:17], v[16:17], v[20:21]
	v_exp_f32_e32 v20, v24
	v_exp_f32_e32 v21, v22
	v_add_f32_e32 v20, 1.0, v20
	v_add_f32_e32 v21, 1.0, v21
	v_rcp_f32_e32 v20, v20
	v_rcp_f32_e32 v21, v21
	s_nop 0
	v_pk_mul_f32 v[20:21], v[20:21], v[38:39]

; __device__ __forceinline__ unsigned cvt_pk_bf16(float lo, float hi) { unsigned r; asm volatile("v_cvt_pk_bf16_f32 %0, %1, %2" : "=v"(r) : "v"(lo), "v"(hi)); return r; }
; __device__ __forceinline__ float sigmoid_f(float x) { return __builtin_amdgcn_rcpf(1.0f + __builtin_amdgcn_exp2f(-1.4426950409f * x)); }
; __device__ __forceinline__ float bf_lo(unsigned w) { return __uint_as_float(w << 16); }
; __device__ __forceinline__ float bf_hi(unsigned w) { return __uint_as_float(w & 0xffff0000u); }
;     __device__ __forceinline__ void operator()(const f32x4 (&acc)[2][2][4][2], const Unit& u, int wr, int wc, int fr, int fq) const {
;     ...
;             for (int m = 0; m < 4; ++m) { const size_t off = (size_t)(row0 + ai * HALF + m * 16) * 2048 + col0;
; #pragma unroll
;                 for (int bj = 0; bj < 2; ++bj) { const f32x4 v0 = acc[ai][bj][m][0] + bv[bj][0], v1 = acc[ai][bj][m][1] + bv[bj][1]; float o[8];
;                     if (isA) {
; #pragma unroll
;                         for (int e = 0; e < 4; ++e) { o[e] = 1.0f - __builtin_amdgcn_exp2f(sigmoid_f(v0[e]) * sv[bj][0][e]); o[4 + e] = 1.0f - __builtin_amdgcn_exp2f(sigmoid_f(v1[e]) * sv[bj][1][e]); }
;                     } else {
;                         const u32x4 uw = *(const u32x4*)(UC + off + bj * HALF);
;                         o[0] = sigmoid_f(v0[0]) * bf_lo(uw.x); o[1] = sigmoid_f(v0[1]) * bf_hi(uw.x); o[2] = sigmoid_f(v0[2]) * bf_lo(uw.y); o[3] = sigmoid_f(v0[3]) * bf_hi(uw.y);
;                         o[4] = sigmoid_f(v1[0]) * bf_lo(uw.z); o[5] = sigmoid_f(v1[1]) * bf_hi(uw.z); o[6] = sigmoid_f(v1[2]) * bf_lo(uw.w); o[7] = sigmoid_f(v1[3]) * bf_hi(uw.w);
;                     }
;                     u32x4 w; w.x = cvt_pk_bf16(o[0], o[1]); w.y = cvt_pk_bf16(o[2], o[3]); w.z = cvt_pk_bf16(o[4], o[5]); w.w = cvt_pk_bf16(o[6], o[7]);
;                     if (isA) *(u32x4*)(OMA + off + bj * HALF) = w; else *(u32x4*)(GI + off + bj * HALF) = w; } }
.LBB0_399:
	v_pk_add_f32 v[8:9], v[8:9], v[32:33]
	v_pk_add_f32 v[6:7], v[6:7], v[30:31]
	v_pk_add_f32 v[4:5], v[4:5], v[28:29]
	v_pk_add_f32 v[2:3], v[2:3], v[26:27]
	v_cvt_pk_bf16_f32 v22, v12, v13
	v_cvt_pk_bf16_f32 v23, v14, v15
	v_cvt_pk_bf16_f32 v24, v16, v17
	v_cvt_pk_bf16_f32 v25, v20, v21
	v_lshl_add_u64 v[12:13], v[18:19], 1, s[44:45]
	s_mov_b64 s[10:11], -1
	s_and_b64 vcc, exec, s[40:41]
	v_mul_f32_e32 v21, 0xbfb8aa3b, v6
	v_mul_f32_e32 v19, 0xbfb8aa3b, v7
	v_mul_f32_e32 v17, 0xbfb8aa3b, v8
	v_mul_f32_e32 v15, 0xbfb8aa3b, v9
	v_mul_f32_e32 v20, 0xbfb8aa3b, v2
	v_mul_f32_e32 v18, 0xbfb8aa3b, v3
	v_mul_f32_e32 v16, 0xbfb8aa3b, v4
	v_mul_f32_e32 v14, 0xbfb8aa3b, v5
	global_store_dwordx4 v[12:13], v[22:25], off
	s_cbranch_vccnz .LBB0_401
	s_nop 0
	v_exp_f32_e32 v2, v21
	v_exp_f32_e32 v3, v19
	s_mov_b64 s[10:11], 0
	v_add_f32_e32 v2, 1.0, v2
	v_add_f32_e32 v3, 1.0, v3
	v_rcp_f32_e32 v2, v2
	v_rcp_f32_e32 v3, v3
	s_waitcnt vmcnt(0)
	v_mov_b64_e32 v[6:7], v[240:241]
	v_mov_b64_e32 v[8:9], v[242:243]
	v_lshlrev_b32_e32 v4, 16, v6
	v_and_b32_e32 v5, 0xffff0000, v6
	v_pk_mul_f32 v[2:3], v[2:3], v[4:5]
	v_exp_f32_e32 v4, v17
	v_exp_f32_e32 v5, v15
	v_lshlrev_b32_e32 v6, 16, v7
	v_and_b32_e32 v7, 0xffff0000, v7
	v_add_f32_e32 v4, 1.0, v4
	v_add_f32_e32 v5, 1.0, v5
	v_rcp_f32_e32 v4, v4
	v_rcp_f32_e32 v5, v5
	v_lshlrev_b32_e32 v10, 16, v8
	v_and_b32_e32 v11, 0xffff0000, v8
	v_exp_f32_e32 v8, v16
	v_pk_mul_f32 v[4:5], v[4:5], v[6:7]
	v_exp_f32_e32 v6, v20
	v_exp_f32_e32 v7, v18
	v_add_f32_e32 v8, 1.0, v8
	v_add_f32_e32 v6, 1.0, v6
	v_add_f32_e32 v7, 1.0, v7
	v_rcp_f32_e32 v6, v6
	v_rcp_f32_e32 v7, v7
	s_nop 0
	v_pk_mul_f32 v[6:7], v[6:7], v[10:11]
	v_rcp_f32_e32 v10, v8
	v_exp_f32_e32 v8, v14
	s_nop 0
	v_add_f32_e32 v8, 1.0, v8
	v_rcp_f32_e32 v11, v8
	v_lshlrev_b32_e32 v8, 16, v9
	v_and_b32_e32 v9, 0xffff0000, v9
	v_pk_mul_f32 v[8:9], v[10:11], v[8:9]
